# speedup vs baseline: 1.0190x; 1.0024x over previous
; DEVI unsigned cvtpk(float lo, float hi) { unsigned r; asm("v_cvt_pk_bf16_f32 %0, %1, %2" : "=v"(r) : "v"(lo), "v"(hi)); return r; }
; template <int EPI> ...
;     ...
;   if (EPI == 5) {
; #pragma unroll
;     for (int ai = 0; ai < 2; ++ai)
; #pragma unroll
;       for (int bj = 0; bj < 2; ++bj)
; #pragma unroll
;         for (int m = 0; m < 4; ++m)
; #pragma unroll
;           for (int n = 0; n < 2; ++n) {
;             const int col = bcol + bj * 128 + wc * 32 + n * 16 + fr;
;             const int row0 = brow + ai * 128 + wr * 64 + m * 16 + fq * 4;
;             const int c = col - 4608, head = c >> 7, e = c & 127;
;             const int bb = row0 >> 14, l0 = row0 & 16383;
;             u16* vrow = o2 + (((size_t)(bb * 6 + head) * 256 + (l0 >> 6)) * 128 + e) * 64 + (l0 & 63);
;             u32x2 w = {cvtpk(acc[ai][bj][m][n][0], acc[ai][bj][m][n][1]), cvtpk(acc[ai][bj][m][n][2], acc[ai][bj][m][n][3])};
;             *(u32x2*)vrow = w;
;           }
.LBB0_184:
	v_add_u32_e32 v164, s37, v153
	v_add_u32_e32 v132, 0xffffee80, v164
	v_add_u32_e32 v165, s36, v154
	v_bfe_u32 v141, v165, 2, 1
	v_bfe_u32 v166, v165, 3, 1
	v_xor_b32_e32 v141, v141, v166
	v_mul_u32_u24_e32 v141, 12, v141
	v_xor_b32_e32 v165, v165, v141
	v_ashrrev_i32_e32 v141, 7, v132
	v_add_u32_e32 v132, 0xffffee00, v164
	v_ashrrev_i32_e32 v166, 7, v132
	v_ashrrev_i32_e32 v167, 14, v165
	v_mad_i32_i24 v142, v167, 6, v166
	v_lshlrev_b32_e32 v132, 1, v165
	v_ashrrev_i32_e32 v143, 31, v142
	v_and_b32_e32 v140, 0x7f, v164
	v_and_b32_e32 v168, 0x7f80, v132
	v_and_b32_e32 v132, 63, v165
	v_lshlrev_b64 v[142:143], 15, v[142:143]
	v_lshlrev_b32_e32 v132, 1, v132
	v_or3_b32 v142, v142, v168, v140
	v_lshl_add_u64 v[138:139], s[6:7], 0, v[132:133]
	v_lshlrev_b64 v[142:143], 7, v[142:143]
	v_lshl_add_u64 v[142:143], v[138:139], 0, v[142:143]
	v_cvt_pk_bf16_f32 v126, v126, v127
	v_cvt_pk_bf16_f32 v127, v128, v129
	global_store_dwordx2 v[142:143], v[126:127], off
	v_add_u32_e32 v127, 0xffffee10, v164
	v_ashrrev_i32_e32 v127, 7, v127
	v_mad_i32_i24 v128, v167, 6, v127
	v_add_u32_e32 v126, 16, v164
	v_ashrrev_i32_e32 v129, 31, v128
	v_and_b32_e32 v126, 0x7f, v126
	v_lshlrev_b64 v[128:129], 15, v[128:129]
	v_or3_b32 v128, v128, v168, v126
	v_lshlrev_b64 v[128:129], 7, v[128:129]
	v_lshl_add_u64 v[128:129], v[138:139], 0, v[128:129]
	v_cvt_pk_bf16_f32 v122, v122, v123
	v_cvt_pk_bf16_f32 v123, v124, v125
	global_store_dwordx2 v[128:129], v[122:123], off
	v_add_u32_e32 v122, 16, v165
	v_ashrrev_i32_e32 v128, 14, v122
	v_mad_i32_i24 v124, v128, 6, v166
	v_lshlrev_b32_e32 v123, 1, v122
	v_ashrrev_i32_e32 v125, 31, v124
	v_and_b32_e32 v129, 0x7f80, v123
	v_and_b32_e32 v122, 63, v122
	v_lshlrev_b64 v[124:125], 15, v[124:125]
	v_lshlrev_b32_e32 v132, 1, v122
	v_or3_b32 v124, v124, v129, v140
	v_lshl_add_u64 v[122:123], s[6:7], 0, v[132:133]
	v_lshlrev_b64 v[124:125], 7, v[124:125]
	v_lshl_add_u64 v[124:125], v[122:123], 0, v[124:125]
	v_cvt_pk_bf16_f32 v118, v118, v119
	v_cvt_pk_bf16_f32 v119, v120, v121
	global_store_dwordx2 v[124:125], v[118:119], off
	v_mad_i32_i24 v118, v128, 6, v127
	v_ashrrev_i32_e32 v119, 31, v118
	v_lshlrev_b64 v[118:119], 15, v[118:119]
	v_or3_b32 v118, v118, v129, v126
	v_lshlrev_b64 v[118:119], 7, v[118:119]
	v_lshl_add_u64 v[118:119], v[122:123], 0, v[118:119]
	v_cvt_pk_bf16_f32 v114, v114, v115
	v_cvt_pk_bf16_f32 v115, v116, v117
	global_store_dwordx2 v[118:119], v[114:115], off
	v_add_u32_e32 v114, 32, v165
	v_ashrrev_i32_e32 v118, 14, v114
	v_mad_i32_i24 v116, v118, 6, v166
	v_lshlrev_b32_e32 v115, 1, v114
	v_ashrrev_i32_e32 v117, 31, v116
	v_and_b32_e32 v119, 0x7f80, v115
	v_and_b32_e32 v114, 63, v114
	v_lshlrev_b64 v[116:117], 15, v[116:117]
	v_lshlrev_b32_e32 v132, 1, v114
	v_or3_b32 v116, v116, v119, v140
	v_lshl_add_u64 v[114:115], s[6:7], 0, v[132:133]
	v_lshlrev_b64 v[116:117], 7, v[116:117]
	v_lshl_add_u64 v[116:117], v[114:115], 0, v[116:117]
	v_cvt_pk_bf16_f32 v110, v110, v111
	v_cvt_pk_bf16_f32 v111, v112, v113
	global_store_dwordx2 v[116:117], v[110:111], off
	v_mad_i32_i24 v110, v118, 6, v127
	v_ashrrev_i32_e32 v111, 31, v110
	v_lshlrev_b64 v[110:111], 15, v[110:111]
	v_or3_b32 v110, v110, v119, v126
	v_lshlrev_b64 v[110:111], 7, v[110:111]
	v_lshl_add_u64 v[110:111], v[114:115], 0, v[110:111]
	v_cvt_pk_bf16_f32 v106, v106, v107
	v_cvt_pk_bf16_f32 v107, v108, v109
	global_store_dwordx2 v[110:111], v[106:107], off
	v_add_u32_e32 v106, 48, v165
	v_ashrrev_i32_e32 v110, 14, v106
	v_mad_i32_i24 v108, v110, 6, v166
	v_lshlrev_b32_e32 v107, 1, v106
	v_ashrrev_i32_e32 v109, 31, v108
	v_and_b32_e32 v111, 0x7f80, v107
	v_and_b32_e32 v106, 63, v106
	v_lshlrev_b64 v[108:109], 15, v[108:109]
	v_lshlrev_b32_e32 v132, 1, v106
	v_or3_b32 v108, v108, v111, v140
	v_lshl_add_u64 v[106:107], s[6:7], 0, v[132:133]
	v_lshlrev_b64 v[108:109], 7, v[108:109]
	v_lshl_add_u64 v[108:109], v[106:107], 0, v[108:109]
	v_cvt_pk_bf16_f32 v102, v102, v103
	v_cvt_pk_bf16_f32 v103, v104, v105
	global_store_dwordx2 v[108:109], v[102:103], off
	v_mad_i32_i24 v102, v110, 6, v127
	v_ashrrev_i32_e32 v103, 31, v102
	v_lshlrev_b64 v[102:103], 15, v[102:103]
	v_or3_b32 v102, v102, v111, v126
	v_lshlrev_b64 v[102:103], 7, v[102:103]
	v_lshl_add_u64 v[102:103], v[106:107], 0, v[102:103]
	v_cvt_pk_bf16_f32 v98, v98, v99
	v_cvt_pk_bf16_f32 v99, v100, v101
	global_store_dwordx2 v[102:103], v[98:99], off
	v_mad_i32_i24 v98, v167, 6, v141
	v_ashrrev_i32_e32 v99, 31, v98
	v_lshlrev_b64 v[98:99], 15, v[98:99]
	v_or3_b32 v98, v98, v168, v140
	v_lshlrev_b64 v[98:99], 7, v[98:99]
	v_lshl_add_u64 v[98:99], v[138:139], 0, v[98:99]
	v_cvt_pk_bf16_f32 v94, v94, v95
	v_cvt_pk_bf16_f32 v95, v96, v97
	global_store_dwordx2 v[98:99], v[94:95], off
	v_add_u32_e32 v94, 0xffffee90, v164
	v_ashrrev_i32_e32 v96, 7, v94
	v_mad_i32_i24 v94, v167, 6, v96
	v_ashrrev_i32_e32 v95, 31, v94
	v_lshlrev_b64 v[94:95], 15, v[94:95]
	v_or3_b32 v94, v94, v168, v126
	v_lshlrev_b64 v[94:95], 7, v[94:95]
	v_lshl_add_u64 v[94:95], v[138:139], 0, v[94:95]
	v_cvt_pk_bf16_f32 v90, v90, v91
	v_cvt_pk_bf16_f32 v91, v92, v93
	global_store_dwordx2 v[94:95], v[90:91], off
	v_mad_i32_i24 v90, v128, 6, v141
	v_ashrrev_i32_e32 v91, 31, v90
	v_lshlrev_b64 v[90:91], 15, v[90:91]
	v_or3_b32 v90, v90, v129, v140
	v_lshlrev_b64 v[90:91], 7, v[90:91]
	v_lshl_add_u64 v[90:91], v[122:123], 0, v[90:91]
	v_cvt_pk_bf16_f32 v86, v86, v87
	v_cvt_pk_bf16_f32 v87, v88, v89
	global_store_dwordx2 v[90:91], v[86:87], off
	v_mad_i32_i24 v86, v128, 6, v96
	v_ashrrev_i32_e32 v87, 31, v86
	v_lshlrev_b64 v[86:87], 15, v[86:87]
	v_or3_b32 v86, v86, v129, v126
	v_lshlrev_b64 v[86:87], 7, v[86:87]
	v_lshl_add_u64 v[86:87], v[122:123], 0, v[86:87]
; DEVI unsigned cvtpk(float lo, float hi) { unsigned r; asm("v_cvt_pk_bf16_f32 %0, %1, %2" : "=v"(r) : "v"(lo), "v"(hi)); return r; }
; template <int EPI> ...
;     ...
;   if (EPI == 5) {
; #pragma unroll
;     for (int ai = 0; ai < 2; ++ai)
; #pragma unroll
;       for (int bj = 0; bj < 2; ++bj)
; #pragma unroll
;         for (int m = 0; m < 4; ++m)
; #pragma unroll
;           for (int n = 0; n < 2; ++n) {
;             const int col = bcol + bj * 128 + wc * 32 + n * 16 + fr;
;             const int row0 = brow + ai * 128 + wr * 64 + m * 16 + fq * 4;
;             const int c = col - 4608, head = c >> 7, e = c & 127;
;             const int bb = row0 >> 14, l0 = row0 & 16383;
;             u16* vrow = o2 + (((size_t)(bb * 6 + head) * 256 + (l0 >> 6)) * 128 + e) * 64 + (l0 & 63);
;             u32x2 w = {cvtpk(acc[ai][bj][m][n][0], acc[ai][bj][m][n][1]), cvtpk(acc[ai][bj][m][n][2], acc[ai][bj][m][n][3])};
;             *(u32x2*)vrow = w;
;           }
	v_cvt_pk_bf16_f32 v82, v82, v83
	v_cvt_pk_bf16_f32 v83, v84, v85
	global_store_dwordx2 v[86:87], v[82:83], off
	v_mad_i32_i24 v82, v118, 6, v141
	v_ashrrev_i32_e32 v83, 31, v82
	v_lshlrev_b64 v[82:83], 15, v[82:83]
	v_or3_b32 v82, v82, v119, v140
	v_lshlrev_b64 v[82:83], 7, v[82:83]
	v_lshl_add_u64 v[82:83], v[114:115], 0, v[82:83]
	v_cvt_pk_bf16_f32 v78, v78, v79
	v_cvt_pk_bf16_f32 v79, v80, v81
	global_store_dwordx2 v[82:83], v[78:79], off
	v_mad_i32_i24 v78, v118, 6, v96
	v_ashrrev_i32_e32 v79, 31, v78
	v_lshlrev_b64 v[78:79], 15, v[78:79]
	v_or3_b32 v78, v78, v119, v126
	v_lshlrev_b64 v[78:79], 7, v[78:79]
	v_lshl_add_u64 v[78:79], v[114:115], 0, v[78:79]
	v_cvt_pk_bf16_f32 v74, v74, v75
	v_cvt_pk_bf16_f32 v75, v76, v77
	global_store_dwordx2 v[78:79], v[74:75], off
	v_mad_i32_i24 v74, v110, 6, v141
	v_ashrrev_i32_e32 v75, 31, v74
	v_lshlrev_b64 v[74:75], 15, v[74:75]
	v_or3_b32 v74, v74, v111, v140
	v_lshlrev_b64 v[74:75], 7, v[74:75]
	v_lshl_add_u64 v[74:75], v[106:107], 0, v[74:75]
	v_cvt_pk_bf16_f32 v70, v70, v71
	v_cvt_pk_bf16_f32 v71, v72, v73
	global_store_dwordx2 v[74:75], v[70:71], off
	v_mad_i32_i24 v70, v110, 6, v96
	v_ashrrev_i32_e32 v71, 31, v70
	v_lshlrev_b64 v[70:71], 15, v[70:71]
	v_or3_b32 v70, v70, v111, v126
	v_lshlrev_b64 v[70:71], 7, v[70:71]
	v_lshl_add_u64 v[70:71], v[106:107], 0, v[70:71]
	v_cvt_pk_bf16_f32 v66, v66, v67
	v_cvt_pk_bf16_f32 v67, v68, v69
	global_store_dwordx2 v[70:71], v[66:67], off
	v_add_u32_e32 v66, 0x80, v165
	v_ashrrev_i32_e32 v68, 14, v66
	v_lshlrev_b32_e32 v66, 1, v66
	v_and_b32_e32 v69, 0x7f80, v66
	v_mad_i32_i24 v66, v68, 6, v166
	v_ashrrev_i32_e32 v67, 31, v66
	v_lshlrev_b64 v[66:67], 15, v[66:67]
	v_or3_b32 v66, v66, v69, v140
	v_lshlrev_b64 v[66:67], 7, v[66:67]
	v_lshl_add_u64 v[66:67], v[138:139], 0, v[66:67]
	v_cvt_pk_bf16_f32 v62, v62, v63
	v_cvt_pk_bf16_f32 v63, v64, v65
	global_store_dwordx2 v[66:67], v[62:63], off
	v_mad_i32_i24 v62, v68, 6, v127
	v_ashrrev_i32_e32 v63, 31, v62
	v_lshlrev_b64 v[62:63], 15, v[62:63]
	v_or3_b32 v62, v62, v69, v126
	v_lshlrev_b64 v[62:63], 7, v[62:63]
	v_lshl_add_u64 v[62:63], v[138:139], 0, v[62:63]
	v_cvt_pk_bf16_f32 v58, v58, v59
	v_cvt_pk_bf16_f32 v59, v60, v61
	global_store_dwordx2 v[62:63], v[58:59], off
	v_add_u32_e32 v58, 0x90, v165
	v_ashrrev_i32_e32 v62, 14, v58
	v_mad_i32_i24 v60, v62, 6, v166
	v_lshlrev_b32_e32 v59, 1, v58
	v_ashrrev_i32_e32 v61, 31, v60
	v_and_b32_e32 v63, 0x7f80, v59
	v_and_b32_e32 v58, 63, v58
	v_lshlrev_b64 v[60:61], 15, v[60:61]
	v_lshlrev_b32_e32 v132, 1, v58
	v_or3_b32 v60, v60, v63, v140
	v_lshl_add_u64 v[58:59], s[6:7], 0, v[132:133]
	v_lshlrev_b64 v[60:61], 7, v[60:61]
	v_lshl_add_u64 v[60:61], v[58:59], 0, v[60:61]
	v_cvt_pk_bf16_f32 v54, v54, v55
	v_cvt_pk_bf16_f32 v55, v56, v57
	global_store_dwordx2 v[60:61], v[54:55], off
	v_mad_i32_i24 v54, v62, 6, v127
	v_ashrrev_i32_e32 v55, 31, v54
	v_lshlrev_b64 v[54:55], 15, v[54:55]
	v_or3_b32 v54, v54, v63, v126
	v_lshlrev_b64 v[54:55], 7, v[54:55]
	v_lshl_add_u64 v[54:55], v[58:59], 0, v[54:55]
	v_cvt_pk_bf16_f32 v50, v50, v51
	v_cvt_pk_bf16_f32 v51, v52, v53
	global_store_dwordx2 v[54:55], v[50:51], off
	v_add_u32_e32 v50, 0xa0, v165
	v_ashrrev_i32_e32 v54, 14, v50
	v_mad_i32_i24 v52, v54, 6, v166
	v_lshlrev_b32_e32 v51, 1, v50
	v_ashrrev_i32_e32 v53, 31, v52
	v_and_b32_e32 v55, 0x7f80, v51
	v_and_b32_e32 v50, 63, v50
	v_lshlrev_b64 v[52:53], 15, v[52:53]
	v_lshlrev_b32_e32 v132, 1, v50
	v_or3_b32 v52, v52, v55, v140
	v_lshl_add_u64 v[50:51], s[6:7], 0, v[132:133]
	v_lshlrev_b64 v[52:53], 7, v[52:53]
	v_lshl_add_u64 v[52:53], v[50:51], 0, v[52:53]
	v_cvt_pk_bf16_f32 v46, v46, v47
	v_cvt_pk_bf16_f32 v47, v48, v49
	global_store_dwordx2 v[52:53], v[46:47], off
	v_mad_i32_i24 v46, v54, 6, v127
	v_ashrrev_i32_e32 v47, 31, v46
	v_lshlrev_b64 v[46:47], 15, v[46:47]
	v_or3_b32 v46, v46, v55, v126
; DEVI unsigned cvtpk(float lo, float hi) { unsigned r; asm("v_cvt_pk_bf16_f32 %0, %1, %2" : "=v"(r) : "v"(lo), "v"(hi)); return r; }
; template <int EPI> ...
;     ...
;   if (EPI == 5) {
; #pragma unroll
;     for (int ai = 0; ai < 2; ++ai)
; #pragma unroll
;       for (int bj = 0; bj < 2; ++bj)
; #pragma unroll
;         for (int m = 0; m < 4; ++m)
; #pragma unroll
;           for (int n = 0; n < 2; ++n) {
;             const int col = bcol + bj * 128 + wc * 32 + n * 16 + fr;
;             const int row0 = brow + ai * 128 + wr * 64 + m * 16 + fq * 4;
;             const int c = col - 4608, head = c >> 7, e = c & 127;
;             const int bb = row0 >> 14, l0 = row0 & 16383;
;             u16* vrow = o2 + (((size_t)(bb * 6 + head) * 256 + (l0 >> 6)) * 128 + e) * 64 + (l0 & 63);
;             u32x2 w = {cvtpk(acc[ai][bj][m][n][0], acc[ai][bj][m][n][1]), cvtpk(acc[ai][bj][m][n][2], acc[ai][bj][m][n][3])};
;             *(u32x2*)vrow = w;
;           }
	v_lshlrev_b64 v[46:47], 7, v[46:47]
	v_lshl_add_u64 v[46:47], v[50:51], 0, v[46:47]
	v_cvt_pk_bf16_f32 v42, v42, v43
	v_cvt_pk_bf16_f32 v43, v44, v45
	global_store_dwordx2 v[46:47], v[42:43], off
	v_add_u32_e32 v42, 0xb0, v165
	v_ashrrev_i32_e32 v46, 14, v42
	v_mad_i32_i24 v44, v46, 6, v166
	v_lshlrev_b32_e32 v43, 1, v42
	v_ashrrev_i32_e32 v45, 31, v44
	v_and_b32_e32 v47, 0x7f80, v43
	v_and_b32_e32 v42, 63, v42
	v_lshlrev_b64 v[44:45], 15, v[44:45]
	v_lshlrev_b32_e32 v132, 1, v42
	v_or3_b32 v44, v44, v47, v140
	v_lshl_add_u64 v[42:43], s[6:7], 0, v[132:133]
	v_lshlrev_b64 v[44:45], 7, v[44:45]
	v_lshl_add_u64 v[44:45], v[42:43], 0, v[44:45]
	v_cvt_pk_bf16_f32 v38, v38, v39
	v_cvt_pk_bf16_f32 v39, v40, v41
	global_store_dwordx2 v[44:45], v[38:39], off
	v_mad_i32_i24 v38, v46, 6, v127
	v_ashrrev_i32_e32 v39, 31, v38
	v_lshlrev_b64 v[38:39], 15, v[38:39]
	v_or3_b32 v38, v38, v47, v126
	v_lshlrev_b64 v[38:39], 7, v[38:39]
	v_lshl_add_u64 v[38:39], v[42:43], 0, v[38:39]
	v_cvt_pk_bf16_f32 v34, v34, v35
	v_cvt_pk_bf16_f32 v35, v36, v37
	global_store_dwordx2 v[38:39], v[34:35], off
	v_mad_i32_i24 v34, v68, 6, v141
	v_ashrrev_i32_e32 v35, 31, v34
	v_lshlrev_b64 v[34:35], 15, v[34:35]
	v_or3_b32 v34, v34, v69, v140
	v_lshlrev_b64 v[34:35], 7, v[34:35]
	v_lshl_add_u64 v[34:35], v[138:139], 0, v[34:35]
	v_cvt_pk_bf16_f32 v30, v30, v31
	v_cvt_pk_bf16_f32 v31, v32, v33
	global_store_dwordx2 v[34:35], v[30:31], off
	v_mad_i32_i24 v30, v68, 6, v96
	v_ashrrev_i32_e32 v31, 31, v30
	v_lshlrev_b64 v[30:31], 15, v[30:31]
	v_or3_b32 v30, v30, v69, v126
	v_lshlrev_b64 v[30:31], 7, v[30:31]
	v_lshl_add_u64 v[30:31], v[138:139], 0, v[30:31]
	v_cvt_pk_bf16_f32 v26, v26, v27
	v_cvt_pk_bf16_f32 v27, v28, v29
	global_store_dwordx2 v[30:31], v[26:27], off
	v_mad_i32_i24 v26, v62, 6, v141
	v_ashrrev_i32_e32 v27, 31, v26
	v_lshlrev_b64 v[26:27], 15, v[26:27]
	v_or3_b32 v26, v26, v63, v140
	v_lshlrev_b64 v[26:27], 7, v[26:27]
	v_lshl_add_u64 v[26:27], v[58:59], 0, v[26:27]
	v_cvt_pk_bf16_f32 v22, v22, v23
	v_cvt_pk_bf16_f32 v23, v24, v25
	global_store_dwordx2 v[26:27], v[22:23], off
	v_mad_i32_i24 v22, v62, 6, v96
	v_ashrrev_i32_e32 v23, 31, v22
	v_lshlrev_b64 v[22:23], 15, v[22:23]
	v_or3_b32 v22, v22, v63, v126
	v_lshlrev_b64 v[22:23], 7, v[22:23]
	v_lshl_add_u64 v[22:23], v[58:59], 0, v[22:23]
	v_cvt_pk_bf16_f32 v18, v18, v19
	v_cvt_pk_bf16_f32 v19, v20, v21
	global_store_dwordx2 v[22:23], v[18:19], off
	v_mad_i32_i24 v18, v54, 6, v141
	v_ashrrev_i32_e32 v19, 31, v18
	v_lshlrev_b64 v[18:19], 15, v[18:19]
	v_or3_b32 v18, v18, v55, v140
	v_lshlrev_b64 v[18:19], 7, v[18:19]
	v_lshl_add_u64 v[18:19], v[50:51], 0, v[18:19]
	v_cvt_pk_bf16_f32 v14, v14, v15
	v_cvt_pk_bf16_f32 v15, v16, v17
	global_store_dwordx2 v[18:19], v[14:15], off
	v_mad_i32_i24 v14, v54, 6, v96
	v_ashrrev_i32_e32 v15, 31, v14
	v_lshlrev_b64 v[14:15], 15, v[14:15]
	v_or3_b32 v14, v14, v55, v126
	v_lshlrev_b64 v[14:15], 7, v[14:15]
	v_lshl_add_u64 v[14:15], v[50:51], 0, v[14:15]
	v_cvt_pk_bf16_f32 v10, v10, v11
	v_cvt_pk_bf16_f32 v11, v12, v13
	global_store_dwordx2 v[14:15], v[10:11], off
	v_mad_i32_i24 v10, v46, 6, v141
	v_ashrrev_i32_e32 v11, 31, v10
	v_lshlrev_b64 v[10:11], 15, v[10:11]
	v_or3_b32 v10, v10, v47, v140
	v_lshlrev_b64 v[10:11], 7, v[10:11]
	v_lshl_add_u64 v[10:11], v[42:43], 0, v[10:11]
	v_cvt_pk_bf16_f32 v6, v6, v7
	v_cvt_pk_bf16_f32 v7, v8, v9
	global_store_dwordx2 v[10:11], v[6:7], off
	v_mad_i32_i24 v6, v46, 6, v96
	v_ashrrev_i32_e32 v7, 31, v6
	v_lshlrev_b64 v[6:7], 15, v[6:7]
	v_or3_b32 v6, v6, v47, v126
	v_lshlrev_b64 v[6:7], 7, v[6:7]
	v_lshl_add_u64 v[6:7], v[42:43], 0, v[6:7]
	s_andn2_b64 vcc, exec, s[62:63]
	s_mov_b32 s34, s35
	v_cvt_pk_bf16_f32 v2, v2, v3
	v_cvt_pk_bf16_f32 v3, v4, v5
	global_store_dwordx2 v[6:7], v[2:3], off
	s_waitcnt vmcnt(0) lgkmcnt(0)
	s_barrier
	s_cbranch_vccz .LBB0_217

; DEVI void attn_item(const Params& p, const int l, const int bh, const int qblk, const float lam, const float osc, char* smem) {
;   const int tid = threadIdx.x, wid = tid >> 6, lane = tid & 63, l31 = lane & 31, hi = lane >> 5;
;   const int b = bh / 6, h = bh % 6;
;   const int qg = wid >> 1, m = wid & 1;
;   const int nkt = 2 * qblk + 2;
;   const int my_last = 2 * qblk + (qg >> 1);
;   const u16* PBC = (const u16*)(p.ws + OFF_PBC);
;   const u16* VT = (const u16*)(p.ws + OFF_VT) + (size_t)(b * 6 + h) * 256 * 8192;
;   const u16* KT = (const u16*)(p.ws + OFF_KT) + (size_t)(b * 6 + h) * 256 * 8192;
;   const size_t tok0 = (size_t)b * SEQ_;
;   float* wsc = (float*)smem + wid * 64;
;   char* stg = smem + 2048;
;   float* obuf = (float*)(smem + 2048);
;   constexpr float C = 0.125f * 1.4426950408889634f;
;   bf16x8 qf[4];
;   {
;     const u16* qp = PBC + (tok0 + (size_t)qblk * 128 + qg * 32 + l31) * 1280 + 512 + h * 128 + m * 64 + hi * 8;
; #pragma unroll
;     for (int d0 = 0; d0 < 4; ++d0) qf[d0] = *(const bf16x8*)(qp + d0 * 16);
;   }
;   const int kkey = tid >> 4, kch = tid & 15;
;   const u16* kg = KT + kkey * 128 + kch * 8;
;   const int klds = (kch >> 3) * 8192 + swz(kkey, kch & 7);
;   const int ve = tid >> 3, vj = tid & 7;
;   const u16* vg = VT + ve * 64 + vj * 8;
;   const int vx = (ve >> 1) & 7;
;   const int vlds0 = 16384 + ve * 128 + ((((vj >> 1) * 2 + 0) ^ vx) << 4) + (vj & 1) * 8;
;   const int vlds1 = 16384 + ve * 128 + ((((vj >> 1) * 2 + 1) ^ vx) << 4) + (vj & 1) * 8;
;   bf16x8 sk0, sk1, sv0, sv1;
;   char* kbuf = stg; char* vbuf = stg + 32768;
;     ...
;   for (int i = 0; i < 64; ++i) { d1 += p.in[25][l * 64 + i] * p.in[26][l * 64 + i]; d2 += p.in[27][l * 64 + i] * p.in[28][l * 64 + i]; }
;   const float lam_init = 0.8f - 0.6f * expf(-0.3f * (float)l);
;   const float lam = expf(d1) - expf(d2) + lam_init;
;   const float osc = 1.f - lam_init;
.LBB0_527:
	s_add_u32 s2, s14, s0
	s_addc_u32 s3, s15, s1
	global_load_dwordx4 v[4:7], v1, s[2:3]
	global_load_dwordx4 v[8:11], v1, s[2:3] offset:16
	s_add_u32 s2, s16, s0
	s_addc_u32 s3, s17, s1
	global_load_dwordx4 v[12:15], v1, s[2:3]
	global_load_dwordx4 v[16:19], v1, s[2:3] offset:16
	s_add_u32 s2, s18, s0
	s_addc_u32 s3, s19, s1
	global_load_dwordx4 v[20:23], v1, s[2:3]
	global_load_dwordx4 v[24:27], v1, s[2:3] offset:16
	s_add_u32 s2, s20, s0
	s_addc_u32 s3, s21, s1
	global_load_dwordx4 v[28:31], v1, s[2:3]
	global_load_dwordx4 v[32:35], v1, s[2:3] offset:16
	s_add_u32 s0, s0, 32
	s_addc_u32 s1, s1, 0
	s_cmpk_eq_i32 s0, 0x100
	s_waitcnt vmcnt(7)
	v_mov_b32_e32 v36, v4
	v_mov_b32_e32 v4, v6
	s_waitcnt vmcnt(6)
	v_mov_b32_e32 v6, v8
	v_mov_b32_e32 v8, v10
	s_waitcnt vmcnt(5)
	v_mov_b32_e32 v10, v12
	v_mov_b32_e32 v12, v14
	s_waitcnt vmcnt(3)
	v_mov_b32_e32 v37, v20
	v_mov_b32_e32 v20, v5
	v_mov_b32_e32 v5, v22
	v_mov_b32_e32 v22, v7
	s_waitcnt vmcnt(2)
	v_mov_b32_e32 v7, v24
	v_mov_b32_e32 v24, v9
	v_mov_b32_e32 v9, v26
	v_mov_b32_e32 v26, v11
	s_waitcnt vmcnt(1)
	v_mov_b32_e32 v11, v28
	v_mov_b32_e32 v28, v13
	v_pk_fma_f32 v[2:3], v[36:37], v[10:11], v[2:3]
	v_mov_b32_e32 v13, v30
	v_pk_fma_f32 v[2:3], v[20:21], v[28:29], v[2:3]
	v_mov_b32_e32 v30, v15
	v_pk_fma_f32 v[2:3], v[4:5], v[12:13], v[2:3]
	v_mov_b32_e32 v14, v16
	s_waitcnt vmcnt(0)
	v_mov_b32_e32 v15, v32
	v_pk_fma_f32 v[2:3], v[22:23], v[30:31], v[2:3]
	v_mov_b32_e32 v32, v17
	v_pk_fma_f32 v[2:3], v[6:7], v[14:15], v[2:3]
	v_mov_b32_e32 v16, v18
	v_mov_b32_e32 v17, v34
	v_pk_fma_f32 v[2:3], v[24:25], v[32:33], v[2:3]
	v_mov_b32_e32 v34, v19
	v_pk_fma_f32 v[2:3], v[8:9], v[16:17], v[2:3]
	s_nop 0
	v_pk_fma_f32 v[2:3], v[26:27], v[34:35], v[2:3]
	s_cbranch_scc0 .LBB0_527
	v_mul_f32_e32 v1, 0x3fb8aa3b, v2
	s_mov_b32 s0, 0x3fb8aa3b
	v_rndne_f32_e32 v4, v1
	v_sub_f32_e32 v5, v1, v4
	v_fma_f32 v1, v2, s0, -v1
	v_fmac_f32_e32 v1, 0x32a5705f, v2
	v_add_f32_e32 v1, v5, v1
	v_exp_f32_e32 v1, v1
	v_cvt_i32_f32_e32 v4, v4
	s_mov_b32 s1, 0xc2ce8ed0
	v_cmp_ngt_f32_e32 vcc, s1, v2
	s_mov_b32 s2, 0x42b17218
	v_ldexp_f32 v1, v1, v4
	v_mul_f32_e32 v4, 0x3fb8aa3b, v3
	v_rndne_f32_e32 v5, v4
	v_sub_f32_e32 v6, v4, v5
	v_fma_f32 v4, v3, s0, -v4
	v_fmac_f32_e32 v4, 0x32a5705f, v3
	v_add_f32_e32 v4, v6, v4
	v_exp_f32_e32 v4, v4
	v_cvt_i32_f32_e32 v5, v5
	v_cndmask_b32_e32 v1, 0, v1, vcc
	v_mov_b32_e32 v6, 0x7f800000
	v_cmp_nlt_f32_e32 vcc, s2, v2
	v_ldexp_f32 v2, v4, v5
	v_bfe_u32 v9, v0, 4, 6
	v_cndmask_b32_e32 v1, v6, v1, vcc
	v_cmp_ngt_f32_e32 vcc, s1, v3
	v_lshlrev_b32_e32 v10, 7, v9
	v_and_b32_e32 v14, 6, v0
	v_cndmask_b32_e32 v2, 0, v2, vcc
	v_cmp_nlt_f32_e32 vcc, s2, v3
	s_movk_i32 s2, 0x3ff
	v_bfe_u32 v3, v0, 5, 5
	v_cndmask_b32_e32 v2, v6, v2, vcc
	v_sub_f32_e32 v1, v1, v2
	v_bitop3_b32 v6, v3, v0, s2 bitop3:0x78
	v_add_f32_e32 v196, 0x3e4ccccc, v1
	v_and_b32_e32 v1, 0x3ff, v0
	v_lshlrev_b32_e32 v6, 4, v6
	v_lshl_or_b32 v12, v1, 10, v6
	s_movk_i32 s2, 0x2070
	v_and_or_b32 v17, v12, s2, v10
	v_bfe_u32 v10, v0, 1, 3
	v_bfe_u32 v195, v1, 5, 1
	v_bitop3_b32 v3, v3, v10, 1 bitop3:0x6c
	v_lshlrev_b32_e32 v202, 4, v3
	v_bitop3_b32 v3, v195, v10, 2 bitop3:0x36
	v_lshlrev_b32_e32 v203, 4, v3
	v_bitop3_b32 v3, v195, v10, 4 bitop3:0x36
	v_and_b32_e32 v166, 31, v0
	v_bfe_u32 v168, v0, 2, 8
	v_lshlrev_b32_e32 v11, 3, v1
	v_lshlrev_b32_e32 v16, 4, v1
	v_bitop3_b32 v15, v9, v14, 7 bitop3:0x6c
	v_lshlrev_b32_e32 v204, 4, v3
	v_bitop3_b32 v3, v195, v10, 6 bitop3:0x36
	v_and_b32_e32 v8, 0x60, v168
	v_mov_b32_e32 v173, 0
	v_bfe_u32 v13, v1, 4, 3
	v_and_b32_e32 v6, 0x1f80, v16
	v_lshlrev_b32_e32 v15, 4, v15
	v_and_b32_e32 v198, 8, v11
	v_lshlrev_b32_e32 v205, 4, v3
	v_lshlrev_b32_e32 v199, 2, v166
	v_and_b32_e32 v3, 64, v1
	v_lshlrev_b32_e32 v172, 8, v9
	v_bfe_u32 v5, v1, 6, 1
	v_and_b32_e32 v7, 0x1c0, v0
	v_bitop3_b32 v11, v14, v13, 1 bitop3:0x36
	v_or3_b32 v18, v15, v6, v198
	v_lshl_add_u32 v200, v166, 7, 16
	v_cmp_ne_u32_e64 s[6:7], 0, v3
	v_lshl_or_b32 v3, v195, 2, v8
	v_add_u32_e32 v171, 16, v199
	s_movk_i32 s8, 0x240
	v_lshl_add_u64 v[12:13], s[28:29], 0, v[172:173]
	v_and_b32_e32 v14, 0xf0, v16
	v_mov_b32_e32 v15, v173
	v_lshlrev_b32_e32 v2, 6, v5
	v_lshl_add_u32 v201, v5, 13, v200
	v_lshl_add_u32 v206, v7, 2, 16
	v_cmp_eq_u32_e64 s[4:5], 0, v5
	v_mad_u32_u24 v208, v3, s8, v171
	v_and_b32_e32 v3, 3, v0
	v_mad_u32_u24 v5, v168, s8, 16
	v_lshl_add_u64 v[12:13], v[12:13], 0, v[14:15]
	s_mov_b64 s[8:9], 0x22a00000
	v_mov_b32_e32 v7, v173
	v_or_b32_e32 v170, v8, v166
	v_lshlrev_b32_e32 v11, 4, v11
	v_lshlrev_b32_e32 v8, 4, v3
	v_lshlrev_b32_e32 v10, 2, v3
	v_lshl_add_u64 v[174:175], v[12:13], 0, s[8:9]
	v_lshl_add_u64 v[12:13], s[28:29], 0, v[6:7]
	v_and_b32_e32 v14, 0x70, v16
	v_and_b32_e32 v3, 15, v0
	s_add_u32 s10, s28, 0x3dd80000
	v_lshlrev_b32_e32 v4, 3, v195
	v_or3_b32 v11, v11, v6, v198
	v_lshl_add_u64 v[12:13], v[12:13], 0, v[14:15]
	s_mov_b64 s[8:9], 0x25a00000
	v_mov_b32_e32 v9, v173
	v_lshl_or_b32 v180, v3, 4, v172
	v_and_b32_e32 v3, 7, v0
	v_lshlrev_b32_e32 v184, 1, v2
	v_mbcnt_lo_u32_b32 v2, -1, 0
	s_mov_b32 s73, 0
	s_addc_u32 s34, s29, 0
	v_cmp_eq_u32_e64 s[0:1], 0, v1
	v_bfe_u32 v167, v0, 6, 4
	v_bfe_u32 v197, v0, 8, 2
	v_cmp_eq_u32_e64 s[2:3], 0, v195
	v_add_u32_e32 v207, v206, v199
	v_lshlrev_b32_e32 v194, 4, v195
	v_mov_b32_e32 v169, v173
	v_lshl_add_u64 v[176:177], v[12:13], 0, s[8:9]
	v_lshl_add_u64 v[178:179], s[22:23], 0, v[8:9]
	v_mov_b32_e32 v181, v173
	v_lshl_or_b32 v182, v3, 4, v6
	v_mov_b32_e32 v183, v173
	v_lshlrev_b32_e32 v186, 1, v4
	s_movk_i32 s35, 0x2000
	s_mov_b32 s36, 0x42800000
	s_mov_b32 s78, 0x3e38aa3b
	v_add_u32_e32 v209, v5, v8
	v_mov_b32_e32 v210, 0x3727c5ac
	v_lshlrev_b32_e32 v172, 1, v10
	v_mov_b32_e32 v211, 0xa00
	v_add_u32_e32 v212, 16, v17
	v_add_u32_e32 v213, 16, v18
	v_add_u32_e32 v214, 16, v11
	v_mbcnt_hi_u32_b32 v193, -1, v2
	s_mov_b32 s37, 0
	v_lshrrev_b32_e32 v180, 3, v0
	v_bfe_u32 v181, v0, 4, 3
	v_and_b32_e32 v188, 7, v0
	v_xor_b32_e32 v181, v188, v181
	v_lshlrev_b32_e32 v180, 8, v180
	v_lshl_or_b32 v180, v181, 4, v180
	v_mov_b32_e32 v181, 0
	v_readfirstlane_b32 s101, v0
	s_lshr_b32 s101, s101, 6
	s_lshl_b32 s101, s101, 10
	v_lshrrev_b32_e32 v253, 3, v0
	v_bfe_u32 v190, v0, 4, 3
	v_and_b32_e32 v191, 7, v0
	v_xor_b32_e32 v190, v191, v190
	v_lshlrev_b32_e32 v253, 7, v253
	v_lshl_or_b32 v182, v190, 4, v253
	v_mov_b32_e32 v183, 0
	v_add_u32_e32 v253, 16, v182
	s_branch .LBB0_530

; #define K_LOAD(kt) do { sk0 = *(const bf16x8*)(kg + (size_t)(kt) * 8192); sk1 = *(const bf16x8*)(kg + (size_t)(kt) * 8192 + 4096); } while (0)
; #define V_LOAD(kt) do { sv0 = *(const bf16x8*)(vg + (size_t)(kt) * 8192); sv1 = *(const bf16x8*)(vg + (size_t)(kt) * 8192 + 4096); } while (0)
; #define K_STORE(bi) do { char* s_ = kbuf + (bi) * 16384; *(bf16x8*)(s_ + klds) = sk0; *(bf16x8*)(s_ + klds + 4096) = sk1; } while (0)
; DEVI void attn_item(const Params& p, const int l, const int bh, const int qblk, const float lam, const float osc, char* smem) {
;     ...
;   bf16x8 qf[4];
;   {
;     const u16* qp = PBC + (tok0 + (size_t)qblk * 128 + qg * 32 + l31) * 1280 + 512 + h * 128 + m * 64 + hi * 8;
; #pragma unroll
;     for (int d0 = 0; d0 < 4; ++d0) qf[d0] = *(const bf16x8*)(qp + d0 * 16);
;   }
;   const int kkey = tid >> 4, kch = tid & 15;
;   const u16* kg = KT + kkey * 128 + kch * 8;
;   const int klds = (kch >> 3) * 8192 + swz(kkey, kch & 7);
;   const int ve = tid >> 3, vj = tid & 7;
;   const u16* vg = VT + ve * 64 + vj * 8;
;   const int vx = (ve >> 1) & 7;
;   const int vlds0 = 16384 + ve * 128 + ((((vj >> 1) * 2 + 0) ^ vx) << 4) + (vj & 1) * 8;
;   const int vlds1 = 16384 + ve * 128 + ((((vj >> 1) * 2 + 1) ^ vx) << 4) + (vj & 1) * 8;
;   bf16x8 sk0, sk1, sv0, sv1;
;   char* kbuf = stg; char* vbuf = stg + 32768;
;     ...
;   f32x16 o[4];
; #pragma unroll
;   for (int d0 = 0; d0 < 4; ++d0)
; #pragma unroll
;     for (int r = 0; r < 16; ++r) o[d0][r] = 0.f;
;   float m_reg = -1e30f, l_reg = 0.f;
;   const int xq = (l31 >> 1) & 7;
;   f32x16 pA0, pA1, pB0, pB1;
;   K_LOAD(0); V_LOAD(0);
;   {
;     const bf16x8 tk0 = *(const bf16x8*)(kg + (size_t)8192), tk1 = *(const bf16x8*)(kg + (size_t)8192 + 4096);
;     K_STORE(0); V_STORE(0);
;     sk0 = tk0; sk1 = tk1; K_STORE(1);
;   }
;   __syncthreads();
;   QK_TILE(pA0, pA1, 0);
;   __syncthreads();
;     ...
;         if (threadIdx.x == 0) s_item = atomicAdd(cnt + q, 1);
;         __syncthreads();
;         const int item = s_item;
;         __syncthreads();
;         if (item >= 192) break;
;         int bh, qblk;
;         if (item < 128) { bh = q; qblk = 127 - item; }
;         else { bh = 8 + (q >> 1); qblk = 127 - 2 * (item - 128) - (q & 1); }
;         attn_item(p, l, bh, qblk, lam, osc, smem);
.LBB0_537:
	s_or_b64 exec, exec, s[8:9]
	s_waitcnt lgkmcnt(0)
	s_barrier
	ds_read_b32 v2, v173
	s_movk_i32 s8, 0xbf
	s_waitcnt lgkmcnt(0)
	s_barrier
	v_cmp_lt_i32_e32 vcc, s8, v2
	v_readfirstlane_b32 s52, v2
	s_mov_b64 s[8:9], -1
	s_cbranch_vccnz .LBB0_532
	s_lshl_b32 s9, s52, 1
	s_or_b32 s9, s9, s87
	s_sub_i32 s8, 0x7f, s52
	s_sub_i32 s9, 0x17f, s9
	s_cmpk_lt_i32 s52, 0x80
	s_cselect_b32 s72, s8, s9
	s_cselect_b32 s52, s79, s86
	s_lshl_b32 s88, s72, 1
	s_cmp_gt_u32 s52, 5
	s_cselect_b32 s53, 0x4000, 0
	s_lshl_b64 s[8:9], s[72:73], 7
	s_add_u32 s84, s8, s53
	s_addc_u32 s85, s9, 0
	s_lshl_b32 s8, s52, 7
	s_add_i32 s9, s8, 0xfffffd00
	s_cmp_lt_u32 s52, 6
	s_cselect_b32 s72, s8, s9
	s_lshl_b32 s8, s52, 22
	s_mov_b32 s9, s73
	v_lshl_add_u64 v[20:21], v[174:175], 0, s[8:9]
	v_add_co_u32_e32 v12, vcc, s35, v20
	v_lshl_add_u64 v[10:11], v[176:177], 0, s[8:9]
	s_nop 0
	v_addc_co_u32_e32 v13, vcc, 0, v21, vcc
	v_add_co_u32_e32 v14, vcc, s35, v10
	s_movk_i32 s9, 0x4000
	s_nop 0
	v_addc_co_u32_e32 v15, vcc, 0, v11, vcc
	v_add_co_u32_e32 v22, vcc, s9, v20
	s_movk_i32 s9, 0x6000
	s_nop 0
	v_addc_co_u32_e32 v23, vcc, 0, v21, vcc
	v_or_b32_e32 v24, s84, v170
	v_mov_b64_e32 v[18:19], s[28:29]
	global_load_dwordx4 v[2:5], v[20:21], off
	global_load_dwordx4 v[6:9], v[10:11], off
	v_add_co_u32_e32 v20, vcc, s9, v20
	s_movk_i32 s9, 0xa00
	v_mad_u64_u32 v[18:19], s[52:53], v24, s9, v[18:19]
	v_mad_u32_u24 v19, s85, v211, v19
	global_load_dwordx4 v[10:13], v[12:13], off
	s_nop 0
	global_load_dwordx4 v[14:17], v[14:15], off
	v_addc_co_u32_e32 v21, vcc, 0, v21, vcc
	global_load_dwordx4 v[146:149], v[22:23], off
	global_load_dwordx4 v[150:153], v[20:21], off
	v_lshl_add_u64 v[18:19], s[72:73], 1, v[18:19]
	v_mov_b32_e32 v185, v173
	v_lshl_add_u64 v[18:19], v[18:19], 0, v[184:185]
	v_mov_b32_e32 v187, v173
	v_lshl_add_u64 v[18:19], v[18:19], 0, v[186:187]
	s_mov_b32 s9, 0x1da00000
	v_add_co_u32_e32 v20, vcc, s9, v18
	s_mov_b64 s[52:53], 0x1da00400
	s_nop 0
	v_addc_co_u32_e32 v21, vcc, 0, v19, vcc
	global_load_dwordx4 v[130:133], v[20:21], off offset:1024
	v_lshl_add_u64 v[18:19], v[18:19], 0, s[52:53]
	global_load_dwordx4 v[134:137], v[18:19], off offset:32
	global_load_dwordx4 v[138:141], v[18:19], off offset:64
	global_load_dwordx4 v[142:145], v[18:19], off offset:96
	v_add_u32_e32 v185, v201, v202
	v_add_u32_e32 v187, v201, v203
	v_add_u32_e32 v215, v201, v204
	v_add_u32_e32 v216, v201, v205
	s_mov_b32 s52, 0
	s_mov_b32 s53, s52
	s_mov_b32 s54, s52
	s_mov_b32 s55, s52
	s_mov_b32 s56, s52
	s_mov_b32 s57, s52
	s_mov_b32 s58, s52
	s_mov_b32 s59, s52
	s_mov_b32 s60, s52
	s_mov_b32 s61, s52
	s_mov_b32 s62, s52
	s_mov_b32 s63, s52
	s_mov_b32 s64, s52
	s_mov_b32 s65, s52
	s_mov_b32 s66, s52
	s_mov_b32 s67, s52
	v_mov_b64_e32 v[50:51], s[52:53]
	v_mov_b64_e32 v[52:53], s[54:55]
	v_mov_b64_e32 v[54:55], s[56:57]
	v_mov_b64_e32 v[56:57], s[58:59]
	v_mov_b64_e32 v[58:59], s[60:61]
	v_mov_b64_e32 v[60:61], s[62:63]
	v_mov_b64_e32 v[62:63], s[64:65]
	v_mov_b64_e32 v[64:65], s[66:67]
	s_add_i32 s53, s88, 2
	s_add_u32 s54, s28, s8
	v_mov_b64_e32 v[34:35], v[50:51]
	v_mov_b64_e32 v[18:19], v[50:51]
	v_add_u32_e32 v217, s88, v197
	s_addc_u32 s55, s29, 0
	v_mov_b32_e32 v218, 0
	v_mov_b32_e32 v192, 0xf149f2ca
	v_mov_b64_e32 v[36:37], v[52:53]
	v_mov_b64_e32 v[38:39], v[54:55]
	v_mov_b64_e32 v[40:41], v[56:57]
	s_waitcnt vmcnt(9)
	ds_write_b128 v212, v[2:5] offset:2048
	s_waitcnt vmcnt(8)
	ds_write_b128 v253, v[6:9] offset:34816
	s_waitcnt vmcnt(7)
	ds_write_b128 v212, v[10:13] offset:6144
	s_waitcnt vmcnt(6)
	ds_write_b128 v253, v[14:17] offset:43008
	s_waitcnt vmcnt(5)
	ds_write_b128 v212, v[146:149] offset:18432
	s_waitcnt vmcnt(4)
	ds_write_b128 v212, v[150:153] offset:22528
	s_waitcnt lgkmcnt(0)
	s_barrier
	ds_read_b128 v[2:5], v185 offset:2048
	ds_read_b128 v[6:9], v185 offset:6144
	s_waitcnt vmcnt(3) lgkmcnt(1)
	v_mfma_f32_32x32x16_bf16 v[66:81], v[2:5], v[130:133], 0
	v_mov_b64_e32 v[42:43], v[58:59]
	v_mov_b64_e32 v[44:45], v[60:61]
	v_mov_b64_e32 v[46:47], v[62:63]
	v_mov_b64_e32 v[48:49], v[64:65]
	v_mov_b64_e32 v[20:21], v[52:53]
	v_mov_b64_e32 v[22:23], v[54:55]
	v_mov_b64_e32 v[24:25], v[56:57]
	s_waitcnt lgkmcnt(0)
	v_mfma_f32_32x32x16_bf16 v[82:97], v[6:9], v[130:133], 0
	ds_read_b128 v[2:5], v187 offset:2048
	ds_read_b128 v[6:9], v187 offset:6144
	v_mov_b64_e32 v[26:27], v[58:59]
	v_mov_b64_e32 v[28:29], v[60:61]
	v_mov_b64_e32 v[30:31], v[62:63]
	v_mov_b64_e32 v[32:33], v[64:65]
	s_waitcnt vmcnt(2) lgkmcnt(1)
	v_mfma_f32_32x32x16_bf16 v[66:81], v[2:5], v[134:137], v[66:81]
	ds_read_b128 v[2:5], v215 offset:2048
	s_waitcnt lgkmcnt(1)
	v_mfma_f32_32x32x16_bf16 v[82:97], v[6:9], v[134:137], v[82:97]
	ds_read_b128 v[6:9], v215 offset:6144
	s_waitcnt vmcnt(1) lgkmcnt(1)
	v_mfma_f32_32x32x16_bf16 v[66:81], v[2:5], v[138:141], v[66:81]
	ds_read_b128 v[2:5], v216 offset:2048
	s_waitcnt lgkmcnt(1)
	v_mfma_f32_32x32x16_bf16 v[82:97], v[6:9], v[138:141], v[82:97]
	ds_read_b128 v[6:9], v216 offset:6144
	s_waitcnt lgkmcnt(0)
	s_barrier
	s_waitcnt vmcnt(0)
	v_mfma_f32_32x32x16_bf16 v[66:81], v[2:5], v[142:145], v[66:81]
	v_mfma_f32_32x32x16_bf16 v[82:97], v[6:9], v[142:145], v[82:97]
	v_mov_b64_e32 v[2:3], v[50:51]
	v_mov_b64_e32 v[4:5], v[52:53]
	v_mov_b64_e32 v[6:7], v[54:55]
	v_mov_b64_e32 v[8:9], v[56:57]
	v_mov_b64_e32 v[10:11], v[58:59]
	v_mov_b64_e32 v[12:13], v[60:61]
	v_mov_b64_e32 v[14:15], v[62:63]
	v_mov_b64_e32 v[16:17], v[64:65]
	s_branch .LBB0_540

.LBB0_542:
	v_lshl_add_u64 v[190:191], s[54:55], 0, v[182:183]
	v_add_co_u32_e32 v154, vcc, 0x25a04000, v190
	s_nop 1
	v_addc_co_u32_e32 v155, vcc, 0, v191, vcc
	v_add_co_u32_e32 v158, vcc, 0x25a06000, v190
	s_nop 1
	v_addc_co_u32_e32 v159, vcc, 0, v191, vcc
	s_add_u32 m0, s101, 0xc810
	s_nop 0
	global_load_lds_dwordx4 v[154:155], off
	s_add_u32 m0, s101, 0xe810
	s_nop 0
	global_load_lds_dwordx4 v[158:159], off
	v_cmp_le_u32_e32 vcc, s52, v217
	s_and_saveexec_b64 s[8:9], vcc
	s_cbranch_execz .LBB0_548
	ds_read_b128 v[98:101], v185 offset:18432
	ds_read_b128 v[114:117], v185 offset:22528
	s_waitcnt lgkmcnt(1)
	v_mfma_f32_32x32x16_bf16 v[98:113], v[98:101], v[130:133], 0
	ds_read_b128 v[118:121], v187 offset:18432
	ds_read_b128 v[220:223], v187 offset:22528
	s_waitcnt lgkmcnt(1)
	v_mfma_f32_32x32x16_bf16 v[98:113], v[118:121], v[134:137], v[98:113]
	ds_read_b128 v[118:121], v215 offset:18432
	s_waitcnt lgkmcnt(0)
	v_mfma_f32_32x32x16_bf16 v[98:113], v[118:121], v[138:141], v[98:113]
	ds_read_b128 v[118:121], v216 offset:18432
	s_waitcnt lgkmcnt(0)
	v_mfma_f32_32x32x16_bf16 v[98:113], v[118:121], v[142:145], v[98:113]
	v_max_f32_e32 v118, v67, v67
	v_max_f32_e32 v119, v66, v66
	v_max_f32_e32 v118, v119, v118
	v_max3_f32 v118, v118, v68, v69
	v_max3_f32 v118, v118, v70, v71
	v_max3_f32 v118, v118, v72, v73
	v_max3_f32 v118, v118, v74, v75
	v_max3_f32 v118, v118, v76, v77
	v_max3_f32 v118, v118, v78, v79
	v_max3_f32 v219, v118, v80, v81
	v_mfma_f32_32x32x16_bf16 v[114:129], v[114:117], v[130:133], 0
	v_max3_f32 v219, v219, v82, v83
	v_max3_f32 v219, v219, v84, v85
	v_max3_f32 v219, v219, v86, v87
	v_max3_f32 v219, v219, v88, v89
	v_max3_f32 v219, v219, v90, v91
	v_max3_f32 v219, v219, v92, v93
	v_max3_f32 v219, v219, v94, v95
	v_max3_f32 v219, v219, v96, v97
	v_mfma_f32_32x32x16_bf16 v[114:129], v[220:223], v[134:137], v[114:129]
	v_mov_b32_e32 v220, v219
	s_nop 1
	v_permlane32_swap_b32_e32 v219, v220
	v_max_f32_e32 v220, v220, v220
	v_max_f32_e32 v219, v219, v219
	v_max_f32_e32 v219, v219, v220
	v_sub_f32_e32 v220, v219, v192
	v_cmp_ge_f32_e32 vcc, s36, v220
	s_cmp_eq_u64 vcc, exec
	v_max_f32_e32 v220, v192, v192
	s_cselect_b64 vcc, -1, 0
	v_max_f32_e32 v219, v220, v219
	v_cndmask_b32_e32 v219, v219, v192, vcc
	v_sub_f32_e32 v192, v192, v219
	v_mul_f32_e32 v192, 0x3e38aa3b, v192
	v_exp_f32_e32 v220, v192
	v_mul_f32_e32 v192, 0xbe38aa3b, v219
	v_pk_fma_f32 v[96:97], v[96:97], s[78:79], v[192:193] op_sel_hi:[1,0,0]
	ds_read_b128 v[224:227], v215 offset:22528
	v_pk_fma_f32 v[86:87], v[86:87], s[78:79], v[192:193] op_sel_hi:[1,0,0]
	v_pk_fma_f32 v[88:89], v[88:89], s[78:79], v[192:193] op_sel_hi:[1,0,0]
	v_pk_fma_f32 v[90:91], v[90:91], s[78:79], v[192:193] op_sel_hi:[1,0,0]
	v_pk_fma_f32 v[92:93], v[92:93], s[78:79], v[192:193] op_sel_hi:[1,0,0]
	v_pk_fma_f32 v[94:95], v[94:95], s[78:79], v[192:193] op_sel_hi:[1,0,0]
	ds_read_b128 v[162:165], v216 offset:22528
	v_pk_fma_f32 v[84:85], v[84:85], s[78:79], v[192:193] op_sel_hi:[1,0,0]
	s_waitcnt lgkmcnt(1)
	v_mfma_f32_32x32x16_bf16 v[114:129], v[224:227], v[138:141], v[114:129]
	v_fma_f32 v66, v66, s78, v192
	v_fma_f32 v67, v67, s78, v192
	v_fma_f32 v68, v68, s78, v192
	v_fma_f32 v69, v69, s78, v192
	v_exp_f32_e32 v66, v66
	v_exp_f32_e32 v67, v67
	v_exp_f32_e32 v68, v68
	v_exp_f32_e32 v69, v69
	v_pk_fma_f32 v[70:71], v[70:71], s[78:79], v[192:193] op_sel_hi:[1,0,0]
	v_pk_add_f32 v[222:223], v[66:67], 0 op_sel_hi:[1,0]
	v_exp_f32_e32 v70, v70
	v_exp_f32_e32 v71, v71
	v_pk_add_f32 v[222:223], v[68:69], v[222:223]
	v_pk_fma_f32 v[72:73], v[72:73], s[78:79], v[192:193] op_sel_hi:[1,0,0]
	v_exp_f32_e32 v84, v84
	v_pk_add_f32 v[222:223], v[70:71], v[222:223]
	v_exp_f32_e32 v72, v72
	v_exp_f32_e32 v73, v73
	s_waitcnt lgkmcnt(0)
	v_mfma_f32_32x32x16_bf16 v[114:129], v[162:165], v[142:145], v[114:129]
	v_fma_f32 v74, v74, s78, v192
	v_fma_f32 v75, v75, s78, v192
	v_fma_f32 v76, v76, s78, v192
	v_fma_f32 v77, v77, s78, v192
	v_exp_f32_e32 v74, v74
	v_exp_f32_e32 v75, v75
	v_exp_f32_e32 v76, v76
	v_exp_f32_e32 v77, v77
	v_pk_fma_f32 v[78:79], v[78:79], s[78:79], v[192:193] op_sel_hi:[1,0,0]
	v_pk_fma_f32 v[80:81], v[80:81], s[78:79], v[192:193] op_sel_hi:[1,0,0]
	v_exp_f32_e32 v78, v78
	v_exp_f32_e32 v79, v79
	v_pk_add_f32 v[222:223], v[72:73], v[222:223]
	v_exp_f32_e32 v80, v80
	v_exp_f32_e32 v81, v81
	v_pk_fma_f32 v[82:83], v[82:83], s[78:79], v[192:193] op_sel_hi:[1,0,0]
	v_pk_add_f32 v[222:223], v[74:75], v[222:223]
	v_exp_f32_e32 v82, v82
	v_exp_f32_e32 v83, v83
	v_pk_add_f32 v[222:223], v[76:77], v[222:223]
	v_exp_f32_e32 v85, v85
	v_pk_add_f32 v[222:223], v[78:79], v[222:223]
	v_exp_f32_e32 v86, v86
	v_exp_f32_e32 v87, v87
	v_pk_add_f32 v[222:223], v[80:81], v[222:223]
	v_exp_f32_e32 v88, v88
	v_exp_f32_e32 v89, v89
	v_pk_add_f32 v[162:163], v[82:83], v[222:223]
	v_exp_f32_e32 v90, v90
	v_exp_f32_e32 v91, v91
	v_pk_add_f32 v[162:163], v[84:85], v[162:163]
	v_exp_f32_e32 v92, v92
	v_exp_f32_e32 v93, v93
	v_pk_add_f32 v[162:163], v[86:87], v[162:163]
	v_exp_f32_e32 v94, v94
	v_exp_f32_e32 v95, v95
	v_pk_add_f32 v[162:163], v[88:89], v[162:163]
	v_exp_f32_e32 v96, v96
	v_exp_f32_e32 v97, v97
	v_pk_add_f32 v[162:163], v[90:91], v[162:163]
	s_nop 0
	v_pk_add_f32 v[162:163], v[92:93], v[162:163]
	s_nop 0
	v_pk_add_f32 v[162:163], v[94:95], v[162:163]
	s_nop 0
	v_pk_add_f32 v[162:163], v[96:97], v[162:163]
	s_nop 0
	v_pk_add_f32 v[162:163], v[162:163], v[162:163] op_sel:[0,1] op_sel_hi:[1,0]
	s_nop 0
	v_mov_b32_e32 v163, v162
	s_nop 1
	v_permlane32_swap_b32_e32 v162, v163
	s_cbranch_vccnz .LBB0_547
	s_waitcnt lgkmcnt(0)
	s_and_saveexec_b64 s[60:61], s[2:3]
	ds_write_b32 v207, v220
	s_or_b64 exec, exec, s[60:61]
	s_waitcnt lgkmcnt(0)
	v_add_u32_e32 v164, v206, v194
	ds_read_b128 v[222:225], v164 offset:96
	ds_read_b128 v[226:229], v164 offset:64
	ds_read_b128 v[230:233], v164 offset:32
	ds_read_b128 v[234:237], v164
	s_waitcnt lgkmcnt(0)
	s_waitcnt lgkmcnt(3)
	v_pk_mul_f32 v[62:63], v[62:63], v[222:223]
	s_waitcnt lgkmcnt(2)
	v_pk_mul_f32 v[58:59], v[58:59], v[226:227]
	s_waitcnt lgkmcnt(1)
	v_pk_mul_f32 v[54:55], v[54:55], v[230:231]
	v_pk_mul_f32 v[64:65], v[64:65], v[224:225]
	v_pk_mul_f32 v[60:61], v[60:61], v[228:229]
	v_pk_mul_f32 v[56:57], v[56:57], v[232:233]
	s_waitcnt lgkmcnt(0)
	v_pk_mul_f32 v[52:53], v[52:53], v[236:237]
	v_pk_mul_f32 v[50:51], v[50:51], v[234:235]
	v_pk_mul_f32 v[46:47], v[46:47], v[222:223]
	v_pk_mul_f32 v[42:43], v[42:43], v[226:227]
	v_pk_mul_f32 v[38:39], v[38:39], v[230:231]
	v_pk_mul_f32 v[48:49], v[48:49], v[224:225]
	v_pk_mul_f32 v[44:45], v[44:45], v[228:229]
	v_pk_mul_f32 v[40:41], v[40:41], v[232:233]
	v_pk_mul_f32 v[36:37], v[36:37], v[236:237]
	v_pk_mul_f32 v[34:35], v[34:35], v[234:235]
	v_pk_mul_f32 v[30:31], v[30:31], v[222:223]
	v_pk_mul_f32 v[26:27], v[26:27], v[226:227]
	v_pk_mul_f32 v[22:23], v[22:23], v[230:231]
	v_pk_mul_f32 v[32:33], v[32:33], v[224:225]
	v_pk_mul_f32 v[28:29], v[28:29], v[228:229]
	v_pk_mul_f32 v[24:25], v[24:25], v[232:233]
	v_pk_mul_f32 v[20:21], v[20:21], v[236:237]
	v_pk_mul_f32 v[18:19], v[18:19], v[234:235]
	v_pk_mul_f32 v[14:15], v[14:15], v[222:223]
	v_pk_mul_f32 v[10:11], v[10:11], v[226:227]
	v_pk_mul_f32 v[6:7], v[6:7], v[230:231]
	v_pk_mul_f32 v[16:17], v[16:17], v[224:225]
	v_pk_mul_f32 v[12:13], v[12:13], v[228:229]
	v_pk_mul_f32 v[8:9], v[8:9], v[232:233]
	v_pk_mul_f32 v[4:5], v[4:5], v[236:237]
	v_pk_mul_f32 v[2:3], v[2:3], v[234:235]

.LBB0_550:
	s_add_i32 s60, s52, 3
	s_cmp_lt_u32 s60, s53
	s_cselect_b64 s[58:59], -1, 0
	s_cmp_ge_u32 s60, s53
	s_waitcnt vmcnt(0)
	s_waitcnt lgkmcnt(0)
	s_barrier
	s_cbranch_scc0 .LBB0_555
	s_and_b64 vcc, exec, s[8:9]
	s_cbranch_vccz .LBB0_556

.LBB0_556:
	v_add_co_u32_e32 v154, vcc, 0x25a08000, v190
	s_nop 1
	v_addc_co_u32_e32 v155, vcc, 0, v191, vcc
	v_add_co_u32_e32 v158, vcc, 0x25a0a000, v190
	s_nop 1
	v_addc_co_u32_e32 v159, vcc, 0, v191, vcc
	s_add_u32 m0, s101, 0x8810
	s_nop 0
	global_load_lds_dwordx4 v[154:155], off
	s_add_u32 m0, s101, 0xa810
	s_nop 0
	global_load_lds_dwordx4 v[158:159], off
	v_cmp_lt_u32_e32 vcc, s52, v217
	s_and_saveexec_b64 s[60:61], vcc
	s_cbranch_execz .LBB0_553

.LBB0_563:
	s_waitcnt vmcnt(0)
	s_branch .LBB0_539

; DEVI unsigned cvtpk(float lo, float hi) { unsigned r; asm("v_cvt_pk_bf16_f32 %0, %1, %2" : "=v"(r) : "v"(lo), "v"(hi)); return r; }
; template <int EPI> ...
;     ...
;   if (EPI == 5) {
; #pragma unroll
;     for (int ai = 0; ai < 2; ++ai)
; #pragma unroll
;       for (int bj = 0; bj < 2; ++bj)
; #pragma unroll
;         for (int m = 0; m < 4; ++m)
; #pragma unroll
;           for (int n = 0; n < 2; ++n) {
;             const int col = bcol + bj * 128 + wc * 32 + n * 16 + fr;
;             const int row0 = brow + ai * 128 + wr * 64 + m * 16 + fq * 4;
;             const int c = col - 4608, head = c >> 7, e = c & 127;
;             const int bb = row0 >> 14, l0 = row0 & 16383;
;             u16* vrow = o2 + (((size_t)(bb * 6 + head) * 256 + (l0 >> 6)) * 128 + e) * 64 + (l0 & 63);
;             u32x2 w = {cvtpk(acc[ai][bj][m][n][0], acc[ai][bj][m][n][1]), cvtpk(acc[ai][bj][m][n][2], acc[ai][bj][m][n][3])};
;             *(u32x2*)vrow = w;
;           }
.LBB0_960:
	v_add_u32_e32 v165, s37, v154
	v_add_u32_e32 v132, 0xffffee80, v165
	v_add_u32_e32 v166, s36, v155
	v_bfe_u32 v141, v166, 2, 1
	v_bfe_u32 v167, v166, 3, 1
	v_xor_b32_e32 v141, v141, v167
	v_mul_u32_u24_e32 v141, 12, v141
	v_xor_b32_e32 v166, v166, v141
	v_ashrrev_i32_e32 v141, 7, v132
	v_add_u32_e32 v132, 0xffffee00, v165
	v_ashrrev_i32_e32 v167, 7, v132
	v_ashrrev_i32_e32 v168, 14, v166
	v_mad_i32_i24 v142, v168, 6, v167
	v_lshlrev_b32_e32 v132, 1, v166
	v_ashrrev_i32_e32 v143, 31, v142
	v_and_b32_e32 v140, 0x7f, v165
	v_and_b32_e32 v169, 0x7f80, v132
	v_and_b32_e32 v132, 63, v166
	v_lshlrev_b64 v[142:143], 15, v[142:143]
	v_lshlrev_b32_e32 v132, 1, v132
	v_or3_b32 v142, v142, v169, v140
	v_lshl_add_u64 v[138:139], s[4:5], 0, v[132:133]
	v_lshlrev_b64 v[142:143], 7, v[142:143]
	v_lshl_add_u64 v[142:143], v[138:139], 0, v[142:143]
	v_cvt_pk_bf16_f32 v126, v126, v127
	v_cvt_pk_bf16_f32 v127, v128, v129
	global_store_dwordx2 v[142:143], v[126:127], off
	v_add_u32_e32 v127, 0xffffee10, v165
	v_ashrrev_i32_e32 v127, 7, v127
	v_mad_i32_i24 v128, v168, 6, v127
	v_add_u32_e32 v126, 16, v165
	v_ashrrev_i32_e32 v129, 31, v128
	v_and_b32_e32 v126, 0x7f, v126
	v_lshlrev_b64 v[128:129], 15, v[128:129]
	v_or3_b32 v128, v128, v169, v126
	v_lshlrev_b64 v[128:129], 7, v[128:129]
	v_lshl_add_u64 v[128:129], v[138:139], 0, v[128:129]
	v_cvt_pk_bf16_f32 v122, v122, v123
	v_cvt_pk_bf16_f32 v123, v124, v125
	global_store_dwordx2 v[128:129], v[122:123], off
	v_add_u32_e32 v122, 16, v166
	v_ashrrev_i32_e32 v128, 14, v122
	v_mad_i32_i24 v124, v128, 6, v167
	v_lshlrev_b32_e32 v123, 1, v122
	v_ashrrev_i32_e32 v125, 31, v124
	v_and_b32_e32 v129, 0x7f80, v123
	v_and_b32_e32 v122, 63, v122
	v_lshlrev_b64 v[124:125], 15, v[124:125]
	v_lshlrev_b32_e32 v132, 1, v122
	v_or3_b32 v124, v124, v129, v140
	v_lshl_add_u64 v[122:123], s[4:5], 0, v[132:133]
	v_lshlrev_b64 v[124:125], 7, v[124:125]
	v_lshl_add_u64 v[124:125], v[122:123], 0, v[124:125]
	v_cvt_pk_bf16_f32 v118, v118, v119
	v_cvt_pk_bf16_f32 v119, v120, v121
	global_store_dwordx2 v[124:125], v[118:119], off
	v_mad_i32_i24 v118, v128, 6, v127
	v_ashrrev_i32_e32 v119, 31, v118
	v_lshlrev_b64 v[118:119], 15, v[118:119]
	v_or3_b32 v118, v118, v129, v126
	v_lshlrev_b64 v[118:119], 7, v[118:119]
	v_lshl_add_u64 v[118:119], v[122:123], 0, v[118:119]
	v_cvt_pk_bf16_f32 v114, v114, v115
	v_cvt_pk_bf16_f32 v115, v116, v117
	global_store_dwordx2 v[118:119], v[114:115], off
	v_add_u32_e32 v114, 32, v166
	v_ashrrev_i32_e32 v118, 14, v114
	v_mad_i32_i24 v116, v118, 6, v167
	v_lshlrev_b32_e32 v115, 1, v114
	v_ashrrev_i32_e32 v117, 31, v116
	v_and_b32_e32 v119, 0x7f80, v115
	v_and_b32_e32 v114, 63, v114
	v_lshlrev_b64 v[116:117], 15, v[116:117]
	v_lshlrev_b32_e32 v132, 1, v114
	v_or3_b32 v116, v116, v119, v140
	v_lshl_add_u64 v[114:115], s[4:5], 0, v[132:133]
	v_lshlrev_b64 v[116:117], 7, v[116:117]
	v_lshl_add_u64 v[116:117], v[114:115], 0, v[116:117]
	v_cvt_pk_bf16_f32 v110, v110, v111
	v_cvt_pk_bf16_f32 v111, v112, v113
	global_store_dwordx2 v[116:117], v[110:111], off
	v_mad_i32_i24 v110, v118, 6, v127
	v_ashrrev_i32_e32 v111, 31, v110
	v_lshlrev_b64 v[110:111], 15, v[110:111]
	v_or3_b32 v110, v110, v119, v126
	v_lshlrev_b64 v[110:111], 7, v[110:111]
	v_lshl_add_u64 v[110:111], v[114:115], 0, v[110:111]
	v_cvt_pk_bf16_f32 v106, v106, v107
	v_cvt_pk_bf16_f32 v107, v108, v109
	global_store_dwordx2 v[110:111], v[106:107], off
	v_add_u32_e32 v106, 48, v166
	v_ashrrev_i32_e32 v110, 14, v106
	v_mad_i32_i24 v108, v110, 6, v167
	v_lshlrev_b32_e32 v107, 1, v106
	v_ashrrev_i32_e32 v109, 31, v108
	v_and_b32_e32 v111, 0x7f80, v107
	v_and_b32_e32 v106, 63, v106
	v_lshlrev_b64 v[108:109], 15, v[108:109]
	v_lshlrev_b32_e32 v132, 1, v106
	v_or3_b32 v108, v108, v111, v140
	v_lshl_add_u64 v[106:107], s[4:5], 0, v[132:133]
	v_lshlrev_b64 v[108:109], 7, v[108:109]
	v_lshl_add_u64 v[108:109], v[106:107], 0, v[108:109]
	v_cvt_pk_bf16_f32 v102, v102, v103
	v_cvt_pk_bf16_f32 v103, v104, v105
	global_store_dwordx2 v[108:109], v[102:103], off
	v_mad_i32_i24 v102, v110, 6, v127
	v_ashrrev_i32_e32 v103, 31, v102
	v_lshlrev_b64 v[102:103], 15, v[102:103]
	v_or3_b32 v102, v102, v111, v126
	v_lshlrev_b64 v[102:103], 7, v[102:103]
	v_lshl_add_u64 v[102:103], v[106:107], 0, v[102:103]
	v_cvt_pk_bf16_f32 v98, v98, v99
	v_cvt_pk_bf16_f32 v99, v100, v101
	global_store_dwordx2 v[102:103], v[98:99], off
	v_mad_i32_i24 v98, v168, 6, v141
	v_ashrrev_i32_e32 v99, 31, v98
	v_lshlrev_b64 v[98:99], 15, v[98:99]
	v_or3_b32 v98, v98, v169, v140
	v_lshlrev_b64 v[98:99], 7, v[98:99]
	v_lshl_add_u64 v[98:99], v[138:139], 0, v[98:99]
	v_cvt_pk_bf16_f32 v94, v94, v95
	v_cvt_pk_bf16_f32 v95, v96, v97
	global_store_dwordx2 v[98:99], v[94:95], off
	v_add_u32_e32 v94, 0xffffee90, v165
	v_ashrrev_i32_e32 v96, 7, v94
	v_mad_i32_i24 v94, v168, 6, v96
	v_ashrrev_i32_e32 v95, 31, v94
	v_lshlrev_b64 v[94:95], 15, v[94:95]
	v_or3_b32 v94, v94, v169, v126
	v_lshlrev_b64 v[94:95], 7, v[94:95]
	v_lshl_add_u64 v[94:95], v[138:139], 0, v[94:95]
	v_cvt_pk_bf16_f32 v90, v90, v91
	v_cvt_pk_bf16_f32 v91, v92, v93
	global_store_dwordx2 v[94:95], v[90:91], off
	v_mad_i32_i24 v90, v128, 6, v141
	v_ashrrev_i32_e32 v91, 31, v90
	v_lshlrev_b64 v[90:91], 15, v[90:91]
	v_or3_b32 v90, v90, v129, v140
	v_lshlrev_b64 v[90:91], 7, v[90:91]
	v_lshl_add_u64 v[90:91], v[122:123], 0, v[90:91]
	v_cvt_pk_bf16_f32 v86, v86, v87
	v_cvt_pk_bf16_f32 v87, v88, v89
	global_store_dwordx2 v[90:91], v[86:87], off
	v_mad_i32_i24 v86, v128, 6, v96
	v_ashrrev_i32_e32 v87, 31, v86
	v_lshlrev_b64 v[86:87], 15, v[86:87]
	v_or3_b32 v86, v86, v129, v126
	v_lshlrev_b64 v[86:87], 7, v[86:87]
	v_lshl_add_u64 v[86:87], v[122:123], 0, v[86:87]
; DEVI unsigned cvtpk(float lo, float hi) { unsigned r; asm("v_cvt_pk_bf16_f32 %0, %1, %2" : "=v"(r) : "v"(lo), "v"(hi)); return r; }
; template <int EPI> ...
;     ...
;   if (EPI == 5) {
; #pragma unroll
;     for (int ai = 0; ai < 2; ++ai)
; #pragma unroll
;       for (int bj = 0; bj < 2; ++bj)
; #pragma unroll
;         for (int m = 0; m < 4; ++m)
; #pragma unroll
;           for (int n = 0; n < 2; ++n) {
;             const int col = bcol + bj * 128 + wc * 32 + n * 16 + fr;
;             const int row0 = brow + ai * 128 + wr * 64 + m * 16 + fq * 4;
;             const int c = col - 4608, head = c >> 7, e = c & 127;
;             const int bb = row0 >> 14, l0 = row0 & 16383;
;             u16* vrow = o2 + (((size_t)(bb * 6 + head) * 256 + (l0 >> 6)) * 128 + e) * 64 + (l0 & 63);
;             u32x2 w = {cvtpk(acc[ai][bj][m][n][0], acc[ai][bj][m][n][1]), cvtpk(acc[ai][bj][m][n][2], acc[ai][bj][m][n][3])};
;             *(u32x2*)vrow = w;
;           }
	v_cvt_pk_bf16_f32 v82, v82, v83
	v_cvt_pk_bf16_f32 v83, v84, v85
	global_store_dwordx2 v[86:87], v[82:83], off
	v_mad_i32_i24 v82, v118, 6, v141
	v_ashrrev_i32_e32 v83, 31, v82
	v_lshlrev_b64 v[82:83], 15, v[82:83]
	v_or3_b32 v82, v82, v119, v140
	v_lshlrev_b64 v[82:83], 7, v[82:83]
	v_lshl_add_u64 v[82:83], v[114:115], 0, v[82:83]
	v_cvt_pk_bf16_f32 v78, v78, v79
	v_cvt_pk_bf16_f32 v79, v80, v81
	global_store_dwordx2 v[82:83], v[78:79], off
	v_mad_i32_i24 v78, v118, 6, v96
	v_ashrrev_i32_e32 v79, 31, v78
	v_lshlrev_b64 v[78:79], 15, v[78:79]
	v_or3_b32 v78, v78, v119, v126
	v_lshlrev_b64 v[78:79], 7, v[78:79]
	v_lshl_add_u64 v[78:79], v[114:115], 0, v[78:79]
	v_cvt_pk_bf16_f32 v74, v74, v75
	v_cvt_pk_bf16_f32 v75, v76, v77
	global_store_dwordx2 v[78:79], v[74:75], off
	v_mad_i32_i24 v74, v110, 6, v141
	v_ashrrev_i32_e32 v75, 31, v74
	v_lshlrev_b64 v[74:75], 15, v[74:75]
	v_or3_b32 v74, v74, v111, v140
	v_lshlrev_b64 v[74:75], 7, v[74:75]
	v_lshl_add_u64 v[74:75], v[106:107], 0, v[74:75]
	v_cvt_pk_bf16_f32 v70, v70, v71
	v_cvt_pk_bf16_f32 v71, v72, v73
	global_store_dwordx2 v[74:75], v[70:71], off
	v_mad_i32_i24 v70, v110, 6, v96
	v_ashrrev_i32_e32 v71, 31, v70
	v_lshlrev_b64 v[70:71], 15, v[70:71]
	v_or3_b32 v70, v70, v111, v126
	v_lshlrev_b64 v[70:71], 7, v[70:71]
	v_lshl_add_u64 v[70:71], v[106:107], 0, v[70:71]
	v_cvt_pk_bf16_f32 v66, v66, v67
	v_cvt_pk_bf16_f32 v67, v68, v69
	global_store_dwordx2 v[70:71], v[66:67], off
	v_add_u32_e32 v66, 0x80, v166
	v_ashrrev_i32_e32 v68, 14, v66
	v_lshlrev_b32_e32 v66, 1, v66
	v_and_b32_e32 v69, 0x7f80, v66
	v_mad_i32_i24 v66, v68, 6, v167
	v_ashrrev_i32_e32 v67, 31, v66
	v_lshlrev_b64 v[66:67], 15, v[66:67]
	v_or3_b32 v66, v66, v69, v140
	v_lshlrev_b64 v[66:67], 7, v[66:67]
	v_lshl_add_u64 v[66:67], v[138:139], 0, v[66:67]
	v_cvt_pk_bf16_f32 v62, v62, v63
	v_cvt_pk_bf16_f32 v63, v64, v65
	global_store_dwordx2 v[66:67], v[62:63], off
	v_mad_i32_i24 v62, v68, 6, v127
	v_ashrrev_i32_e32 v63, 31, v62
	v_lshlrev_b64 v[62:63], 15, v[62:63]
	v_or3_b32 v62, v62, v69, v126
	v_lshlrev_b64 v[62:63], 7, v[62:63]
	v_lshl_add_u64 v[62:63], v[138:139], 0, v[62:63]
	v_cvt_pk_bf16_f32 v58, v58, v59
	v_cvt_pk_bf16_f32 v59, v60, v61
	global_store_dwordx2 v[62:63], v[58:59], off
	v_add_u32_e32 v58, 0x90, v166
	v_ashrrev_i32_e32 v62, 14, v58
	v_mad_i32_i24 v60, v62, 6, v167
	v_lshlrev_b32_e32 v59, 1, v58
	v_ashrrev_i32_e32 v61, 31, v60
	v_and_b32_e32 v63, 0x7f80, v59
	v_and_b32_e32 v58, 63, v58
	v_lshlrev_b64 v[60:61], 15, v[60:61]
	v_lshlrev_b32_e32 v132, 1, v58
	v_or3_b32 v60, v60, v63, v140
	v_lshl_add_u64 v[58:59], s[4:5], 0, v[132:133]
	v_lshlrev_b64 v[60:61], 7, v[60:61]
	v_lshl_add_u64 v[60:61], v[58:59], 0, v[60:61]
	v_cvt_pk_bf16_f32 v54, v54, v55
	v_cvt_pk_bf16_f32 v55, v56, v57
	global_store_dwordx2 v[60:61], v[54:55], off
	v_mad_i32_i24 v54, v62, 6, v127
	v_ashrrev_i32_e32 v55, 31, v54
	v_lshlrev_b64 v[54:55], 15, v[54:55]
	v_or3_b32 v54, v54, v63, v126
	v_lshlrev_b64 v[54:55], 7, v[54:55]
	v_lshl_add_u64 v[54:55], v[58:59], 0, v[54:55]
	v_cvt_pk_bf16_f32 v50, v50, v51
	v_cvt_pk_bf16_f32 v51, v52, v53
	global_store_dwordx2 v[54:55], v[50:51], off
	v_add_u32_e32 v50, 0xa0, v166
	v_ashrrev_i32_e32 v54, 14, v50
	v_mad_i32_i24 v52, v54, 6, v167
	v_lshlrev_b32_e32 v51, 1, v50
	v_ashrrev_i32_e32 v53, 31, v52
	v_and_b32_e32 v55, 0x7f80, v51
	v_and_b32_e32 v50, 63, v50
	v_lshlrev_b64 v[52:53], 15, v[52:53]
	v_lshlrev_b32_e32 v132, 1, v50
	v_or3_b32 v52, v52, v55, v140
	v_lshl_add_u64 v[50:51], s[4:5], 0, v[132:133]
	v_lshlrev_b64 v[52:53], 7, v[52:53]
	v_lshl_add_u64 v[52:53], v[50:51], 0, v[52:53]
	v_cvt_pk_bf16_f32 v46, v46, v47
	v_cvt_pk_bf16_f32 v47, v48, v49
	global_store_dwordx2 v[52:53], v[46:47], off
	v_mad_i32_i24 v46, v54, 6, v127
	v_ashrrev_i32_e32 v47, 31, v46
	v_lshlrev_b64 v[46:47], 15, v[46:47]
	v_or3_b32 v46, v46, v55, v126
; DEVI unsigned cvtpk(float lo, float hi) { unsigned r; asm("v_cvt_pk_bf16_f32 %0, %1, %2" : "=v"(r) : "v"(lo), "v"(hi)); return r; }
; template <int EPI> ...
;     ...
;   if (EPI == 5) {
; #pragma unroll
;     for (int ai = 0; ai < 2; ++ai)
; #pragma unroll
;       for (int bj = 0; bj < 2; ++bj)
; #pragma unroll
;         for (int m = 0; m < 4; ++m)
; #pragma unroll
;           for (int n = 0; n < 2; ++n) {
;             const int col = bcol + bj * 128 + wc * 32 + n * 16 + fr;
;             const int row0 = brow + ai * 128 + wr * 64 + m * 16 + fq * 4;
;             const int c = col - 4608, head = c >> 7, e = c & 127;
;             const int bb = row0 >> 14, l0 = row0 & 16383;
;             u16* vrow = o2 + (((size_t)(bb * 6 + head) * 256 + (l0 >> 6)) * 128 + e) * 64 + (l0 & 63);
;             u32x2 w = {cvtpk(acc[ai][bj][m][n][0], acc[ai][bj][m][n][1]), cvtpk(acc[ai][bj][m][n][2], acc[ai][bj][m][n][3])};
;             *(u32x2*)vrow = w;
;           }
;     ...
;   __syncthreads();
	v_lshlrev_b64 v[46:47], 7, v[46:47]
	v_lshl_add_u64 v[46:47], v[50:51], 0, v[46:47]
	v_cvt_pk_bf16_f32 v42, v42, v43
	v_cvt_pk_bf16_f32 v43, v44, v45
	global_store_dwordx2 v[46:47], v[42:43], off
	v_add_u32_e32 v42, 0xb0, v166
	v_ashrrev_i32_e32 v46, 14, v42
	v_mad_i32_i24 v44, v46, 6, v167
	v_lshlrev_b32_e32 v43, 1, v42
	v_ashrrev_i32_e32 v45, 31, v44
	v_and_b32_e32 v47, 0x7f80, v43
	v_and_b32_e32 v42, 63, v42
	v_lshlrev_b64 v[44:45], 15, v[44:45]
	v_lshlrev_b32_e32 v132, 1, v42
	v_or3_b32 v44, v44, v47, v140
	v_lshl_add_u64 v[42:43], s[4:5], 0, v[132:133]
	v_lshlrev_b64 v[44:45], 7, v[44:45]
	v_lshl_add_u64 v[44:45], v[42:43], 0, v[44:45]
	v_cvt_pk_bf16_f32 v38, v38, v39
	v_cvt_pk_bf16_f32 v39, v40, v41
	global_store_dwordx2 v[44:45], v[38:39], off
	v_mad_i32_i24 v38, v46, 6, v127
	v_ashrrev_i32_e32 v39, 31, v38
	v_lshlrev_b64 v[38:39], 15, v[38:39]
	v_or3_b32 v38, v38, v47, v126
	v_lshlrev_b64 v[38:39], 7, v[38:39]
	v_lshl_add_u64 v[38:39], v[42:43], 0, v[38:39]
	v_cvt_pk_bf16_f32 v34, v34, v35
	v_cvt_pk_bf16_f32 v35, v36, v37
	global_store_dwordx2 v[38:39], v[34:35], off
	v_mad_i32_i24 v34, v68, 6, v141
	v_ashrrev_i32_e32 v35, 31, v34
	v_lshlrev_b64 v[34:35], 15, v[34:35]
	v_or3_b32 v34, v34, v69, v140
	v_lshlrev_b64 v[34:35], 7, v[34:35]
	v_lshl_add_u64 v[34:35], v[138:139], 0, v[34:35]
	v_cvt_pk_bf16_f32 v30, v30, v31
	v_cvt_pk_bf16_f32 v31, v32, v33
	global_store_dwordx2 v[34:35], v[30:31], off
	v_mad_i32_i24 v30, v68, 6, v96
	v_ashrrev_i32_e32 v31, 31, v30
	v_lshlrev_b64 v[30:31], 15, v[30:31]
	v_or3_b32 v30, v30, v69, v126
	v_lshlrev_b64 v[30:31], 7, v[30:31]
	v_lshl_add_u64 v[30:31], v[138:139], 0, v[30:31]
	v_cvt_pk_bf16_f32 v26, v26, v27
	v_cvt_pk_bf16_f32 v27, v28, v29
	global_store_dwordx2 v[30:31], v[26:27], off
	v_mad_i32_i24 v26, v62, 6, v141
	v_ashrrev_i32_e32 v27, 31, v26
	v_lshlrev_b64 v[26:27], 15, v[26:27]
	v_or3_b32 v26, v26, v63, v140
	v_lshlrev_b64 v[26:27], 7, v[26:27]
	v_lshl_add_u64 v[26:27], v[58:59], 0, v[26:27]
	v_cvt_pk_bf16_f32 v22, v22, v23
	v_cvt_pk_bf16_f32 v23, v24, v25
	global_store_dwordx2 v[26:27], v[22:23], off
	v_mad_i32_i24 v22, v62, 6, v96
	v_ashrrev_i32_e32 v23, 31, v22
	v_lshlrev_b64 v[22:23], 15, v[22:23]
	v_or3_b32 v22, v22, v63, v126
	v_lshlrev_b64 v[22:23], 7, v[22:23]
	v_lshl_add_u64 v[22:23], v[58:59], 0, v[22:23]
	v_cvt_pk_bf16_f32 v18, v18, v19
	v_cvt_pk_bf16_f32 v19, v20, v21
	global_store_dwordx2 v[22:23], v[18:19], off
	v_mad_i32_i24 v18, v54, 6, v141
	v_ashrrev_i32_e32 v19, 31, v18
	v_lshlrev_b64 v[18:19], 15, v[18:19]
	v_or3_b32 v18, v18, v55, v140
	v_lshlrev_b64 v[18:19], 7, v[18:19]
	v_lshl_add_u64 v[18:19], v[50:51], 0, v[18:19]
	v_cvt_pk_bf16_f32 v14, v14, v15
	v_cvt_pk_bf16_f32 v15, v16, v17
	global_store_dwordx2 v[18:19], v[14:15], off
	v_mad_i32_i24 v14, v54, 6, v96
	v_ashrrev_i32_e32 v15, 31, v14
	v_lshlrev_b64 v[14:15], 15, v[14:15]
	v_or3_b32 v14, v14, v55, v126
	v_lshlrev_b64 v[14:15], 7, v[14:15]
	v_lshl_add_u64 v[14:15], v[50:51], 0, v[14:15]
	v_cvt_pk_bf16_f32 v10, v10, v11
	v_cvt_pk_bf16_f32 v11, v12, v13
	global_store_dwordx2 v[14:15], v[10:11], off
	v_mad_i32_i24 v10, v46, 6, v141
	v_ashrrev_i32_e32 v11, 31, v10
	v_lshlrev_b64 v[10:11], 15, v[10:11]
	v_or3_b32 v10, v10, v47, v140
	v_lshlrev_b64 v[10:11], 7, v[10:11]
	v_lshl_add_u64 v[10:11], v[42:43], 0, v[10:11]
	v_cvt_pk_bf16_f32 v6, v6, v7
	v_cvt_pk_bf16_f32 v7, v8, v9
	global_store_dwordx2 v[10:11], v[6:7], off
	v_mad_i32_i24 v6, v46, 6, v96
	v_ashrrev_i32_e32 v7, 31, v6
	v_lshlrev_b64 v[6:7], 15, v[6:7]
	v_or3_b32 v6, v6, v47, v126
	v_lshlrev_b64 v[6:7], 7, v[6:7]
	v_lshl_add_u64 v[6:7], v[42:43], 0, v[6:7]
	s_andn2_b64 vcc, exec, s[64:65]
	s_mov_b32 s34, s35
	v_cvt_pk_bf16_f32 v2, v2, v3
	v_cvt_pk_bf16_f32 v3, v4, v5
	global_store_dwordx2 v[6:7], v[2:3], off
	s_waitcnt vmcnt(0) lgkmcnt(0)
	s_barrier
	s_cbranch_vccz .LBB0_993

; DEVI void attn_item(const Params& p, const int l, const int bh, const int qblk, const float lam, const float osc, char* smem) {
;   const int tid = threadIdx.x, wid = tid >> 6, lane = tid & 63, l31 = lane & 31, hi = lane >> 5;
;   const int b = bh / 6, h = bh % 6;
;   const int qg = wid >> 1, m = wid & 1;
;   const int nkt = 2 * qblk + 2;
;   const int my_last = 2 * qblk + (qg >> 1);
;   const u16* PBC = (const u16*)(p.ws + OFF_PBC);
;   const u16* VT = (const u16*)(p.ws + OFF_VT) + (size_t)(b * 6 + h) * 256 * 8192;
;   const u16* KT = (const u16*)(p.ws + OFF_KT) + (size_t)(b * 6 + h) * 256 * 8192;
;   const size_t tok0 = (size_t)b * SEQ_;
;   float* wsc = (float*)smem + wid * 64;
;   char* stg = smem + 2048;
;   float* obuf = (float*)(smem + 2048);
;   constexpr float C = 0.125f * 1.4426950408889634f;
;   bf16x8 qf[4];
;   {
;     const u16* qp = PBC + (tok0 + (size_t)qblk * 128 + qg * 32 + l31) * 1280 + 512 + h * 128 + m * 64 + hi * 8;
; #pragma unroll
;     for (int d0 = 0; d0 < 4; ++d0) qf[d0] = *(const bf16x8*)(qp + d0 * 16);
;   }
;   const int kkey = tid >> 4, kch = tid & 15;
;   const u16* kg = KT + kkey * 128 + kch * 8;
;   const int klds = (kch >> 3) * 8192 + swz(kkey, kch & 7);
;   const int ve = tid >> 3, vj = tid & 7;
;   const u16* vg = VT + ve * 64 + vj * 8;
;   const int vx = (ve >> 1) & 7;
;   const int vlds0 = 16384 + ve * 128 + ((((vj >> 1) * 2 + 0) ^ vx) << 4) + (vj & 1) * 8;
;   const int vlds1 = 16384 + ve * 128 + ((((vj >> 1) * 2 + 1) ^ vx) << 4) + (vj & 1) * 8;
;     ...
;   float d1 = 0.f, d2 = 0.f;
;   for (int i = 0; i < 64; ++i) { d1 += p.in[25][l * 64 + i] * p.in[26][l * 64 + i]; d2 += p.in[27][l * 64 + i] * p.in[28][l * 64 + i]; }
;   const float lam_init = 0.8f - 0.6f * expf(-0.3f * (float)l);
;   const float lam = expf(d1) - expf(d2) + lam_init;
;   const float osc = 1.f - lam_init;
.LBB0_1303:
	s_add_u32 s2, s14, s0
	s_addc_u32 s3, s15, s1
	global_load_dwordx4 v[6:9], v4, s[2:3] offset:256
	global_load_dwordx4 v[10:13], v4, s[2:3] offset:272
	s_add_u32 s2, s16, s0
	s_addc_u32 s3, s17, s1
	global_load_dwordx4 v[14:17], v4, s[2:3] offset:256
	global_load_dwordx4 v[18:21], v4, s[2:3] offset:272
	s_add_u32 s2, s18, s0
	s_addc_u32 s3, s19, s1
	global_load_dwordx4 v[22:25], v4, s[2:3] offset:256
	global_load_dwordx4 v[26:29], v4, s[2:3] offset:272
	s_add_u32 s2, s20, s0
	s_addc_u32 s3, s21, s1
	global_load_dwordx4 v[30:33], v4, s[2:3] offset:256
	global_load_dwordx4 v[34:37], v4, s[2:3] offset:272
	s_add_u32 s0, s0, 32
	s_addc_u32 s1, s1, 0
	s_cmpk_eq_i32 s0, 0x100
	s_waitcnt vmcnt(0)
	v_mov_b32_e32 v38, v6
	v_mov_b32_e32 v6, v8
	v_mov_b32_e32 v8, v10
	v_mov_b32_e32 v10, v12
	v_mov_b32_e32 v12, v14
	v_mov_b32_e32 v14, v16
	v_mov_b32_e32 v39, v22
	v_mov_b32_e32 v22, v7
	v_mov_b32_e32 v7, v24
	v_mov_b32_e32 v24, v9
	v_mov_b32_e32 v9, v26
	v_mov_b32_e32 v26, v11
	v_mov_b32_e32 v11, v28
	v_mov_b32_e32 v28, v13
	v_mov_b32_e32 v13, v30
	v_mov_b32_e32 v30, v15
	v_pk_fma_f32 v[2:3], v[38:39], v[12:13], v[2:3]
	v_mov_b32_e32 v15, v32
	v_pk_fma_f32 v[2:3], v[22:23], v[30:31], v[2:3]
	v_mov_b32_e32 v32, v17
	v_pk_fma_f32 v[2:3], v[6:7], v[14:15], v[2:3]
	v_mov_b32_e32 v16, v18
	v_mov_b32_e32 v17, v34
	v_pk_fma_f32 v[2:3], v[24:25], v[32:33], v[2:3]
	v_mov_b32_e32 v34, v19
	v_pk_fma_f32 v[2:3], v[8:9], v[16:17], v[2:3]
	v_mov_b32_e32 v18, v20
	v_mov_b32_e32 v19, v36
	v_pk_fma_f32 v[2:3], v[26:27], v[34:35], v[2:3]
	v_mov_b32_e32 v36, v21
	v_pk_fma_f32 v[2:3], v[10:11], v[18:19], v[2:3]
	s_nop 0
	v_pk_fma_f32 v[2:3], v[28:29], v[36:37], v[2:3]
	s_cbranch_scc0 .LBB0_1303
	v_mul_f32_e32 v4, 0x3fb8aa3b, v2
	s_mov_b32 s0, 0x3fb8aa3b
	v_rndne_f32_e32 v5, v4
	v_sub_f32_e32 v6, v4, v5
	v_fma_f32 v4, v2, s0, -v4
	v_fmac_f32_e32 v4, 0x32a5705f, v2
	v_add_f32_e32 v4, v6, v4
	v_exp_f32_e32 v4, v4
	v_cvt_i32_f32_e32 v5, v5
	s_mov_b32 s1, 0xc2ce8ed0
	v_cmp_ngt_f32_e32 vcc, s1, v2
	s_mov_b32 s2, 0x42b17218
	v_ldexp_f32 v4, v4, v5
	v_mul_f32_e32 v5, 0x3fb8aa3b, v3
	v_rndne_f32_e32 v6, v5
	v_sub_f32_e32 v7, v5, v6
	v_fma_f32 v5, v3, s0, -v5
	v_fmac_f32_e32 v5, 0x32a5705f, v3
	v_add_f32_e32 v5, v7, v5
	v_exp_f32_e32 v5, v5
	v_cvt_i32_f32_e32 v6, v6
	v_cndmask_b32_e32 v4, 0, v4, vcc
	v_mov_b32_e32 v7, 0x7f800000
	v_cmp_nlt_f32_e32 vcc, s2, v2
	v_and_b32_e32 v163, 0x3ff, v0
	v_lshlrev_b32_e32 v9, 7, v42
	v_cndmask_b32_e32 v2, v7, v4, vcc
	v_ldexp_f32 v4, v5, v6
	v_cmp_ngt_f32_e32 vcc, s1, v3
	v_bfe_u32 v192, v163, 5, 1
	v_and_b32_e32 v13, 6, v0
	v_cndmask_b32_e32 v4, 0, v4, vcc
	v_cmp_nlt_f32_e32 vcc, s2, v3
	s_movk_i32 s2, 0x3ff
	v_and_b32_e32 v162, 31, v0
	v_cndmask_b32_e32 v3, v7, v4, vcc
	v_sub_f32_e32 v2, v2, v3
	v_bfe_u32 v3, v0, 5, 5
	v_bitop3_b32 v6, v3, v0, s2 bitop3:0x78
	v_lshlrev_b32_e32 v6, 4, v6
	v_lshl_or_b32 v11, v163, 10, v6
	s_movk_i32 s2, 0x2070
	v_and_or_b32 v11, v11, s2, v9
	v_bfe_u32 v9, v0, 1, 3
	v_bitop3_b32 v3, v3, v9, 1 bitop3:0x6c
	v_lshlrev_b32_e32 v199, 4, v3
	v_bitop3_b32 v3, v192, v9, 2 bitop3:0x36
	v_lshlrev_b32_e32 v200, 4, v3
	v_bitop3_b32 v3, v192, v9, 4 bitop3:0x36
	v_bfe_u32 v164, v0, 2, 8
	v_lshlrev_b32_e32 v10, 3, v163
	v_lshlrev_b32_e32 v16, 4, v163
	v_bitop3_b32 v14, v42, v13, 7 bitop3:0x6c
	v_lshlrev_b32_e32 v201, 4, v3
	v_bitop3_b32 v3, v192, v9, 6 bitop3:0x36
	v_and_b32_e32 v8, 0x60, v164
	v_mov_b32_e32 v169, 0
	v_bfe_u32 v12, v163, 4, 3
	v_and_b32_e32 v6, 0x1f80, v16
	v_lshlrev_b32_e32 v14, 4, v14
	v_and_b32_e32 v195, 8, v10
	v_lshlrev_b32_e32 v202, 4, v3
	v_lshlrev_b32_e32 v196, 2, v162
	v_and_b32_e32 v3, 64, v163
	v_lshlrev_b32_e32 v168, 8, v42
	v_bfe_u32 v5, v163, 6, 1
	v_and_b32_e32 v7, 0x1c0, v0
	v_bitop3_b32 v10, v13, v12, 1 bitop3:0x36
	v_or3_b32 v17, v14, v6, v195
	v_lshl_add_u32 v197, v162, 7, 16
	v_cmp_ne_u32_e64 s[6:7], 0, v3
	v_lshl_or_b32 v3, v192, 2, v8
	v_add_u32_e32 v167, 16, v196
	s_movk_i32 s8, 0x240
	v_lshl_add_u64 v[12:13], s[28:29], 0, v[168:169]
	v_and_b32_e32 v14, 0xf0, v16
	v_mov_b32_e32 v15, v169
	v_add_f32_e32 v193, 0x3eb60549, v2
	v_lshlrev_b32_e32 v2, 6, v5
	v_lshlrev_b32_e32 v10, 4, v10
	v_lshl_add_u32 v198, v5, 13, v197
	v_lshl_add_u32 v203, v7, 2, 16
	v_cmp_eq_u32_e64 s[4:5], 0, v5
	v_mad_u32_u24 v205, v3, s8, v167
	v_and_b32_e32 v3, 3, v0
	v_mad_u32_u24 v5, v164, s8, 16
	v_lshl_add_u64 v[12:13], v[12:13], 0, v[14:15]
	s_mov_b64 s[8:9], 0x22a00000
	v_mov_b32_e32 v7, v169
	v_or_b32_e32 v166, v8, v162
	v_or3_b32 v18, v10, v6, v195
	v_lshlrev_b32_e32 v8, 4, v3
	v_lshlrev_b32_e32 v10, 2, v3
	v_lshl_add_u64 v[170:171], v[12:13], 0, s[8:9]
	v_lshl_add_u64 v[12:13], s[28:29], 0, v[6:7]
	v_and_b32_e32 v14, 0x70, v16
	v_and_b32_e32 v3, 15, v0
	s_add_u32 s10, s28, 0x3dd80024
	v_lshlrev_b32_e32 v4, 3, v192
	v_lshl_add_u64 v[12:13], v[12:13], 0, v[14:15]
	s_mov_b64 s[8:9], 0x25a00000
	v_mov_b32_e32 v9, v169
	v_lshl_or_b32 v176, v3, 4, v168
	v_and_b32_e32 v3, 7, v0
	v_lshlrev_b32_e32 v180, 1, v2
	v_mbcnt_lo_u32_b32 v2, -1, 0
	s_mov_b32 s15, 0
	s_addc_u32 s19, s29, 0
	v_cmp_eq_u32_e64 s[0:1], 0, v163
	v_bfe_u32 v194, v0, 8, 2
	v_cmp_eq_u32_e64 s[2:3], 0, v192
	v_add_u32_e32 v204, v203, v196
	v_lshlrev_b32_e32 v191, 4, v192
	v_mov_b32_e32 v165, v169
	v_lshl_add_u64 v[172:173], v[12:13], 0, s[8:9]
	v_lshl_add_u64 v[174:175], s[22:23], 0, v[8:9]
	v_mov_b32_e32 v177, v169
	v_lshl_or_b32 v178, v3, 4, v6
	v_mov_b32_e32 v179, v169
	s_movk_i32 s34, 0xbf
	s_movk_i32 s35, 0x4000
	s_movk_i32 s36, 0xa00
	v_lshlrev_b32_e32 v182, 1, v4
	s_mov_b64 s[16:17], 0x1da00400
	s_mov_b32 s37, 0x1da00000
	s_movk_i32 s68, 0x2000
	s_movk_i32 s69, 0x6000
	s_mov_b32 s70, 0x42800000
	s_mov_b32 s18, 0x3e38aa3b
	v_add_u32_e32 v206, v5, v8
	v_mov_b32_e32 v207, 0x3727c5ac
	s_mov_b32 s71, 0x800000
	v_lshlrev_b32_e32 v168, 1, v10
	s_mov_b64 s[20:21], 0xba00a00
	s_mov_b32 s72, 0xba00000
	v_mov_b32_e32 v208, 0xa00
	v_add_u32_e32 v209, 16, v11
	v_add_u32_e32 v210, 16, v17
	v_add_u32_e32 v211, 16, v18
	v_mbcnt_hi_u32_b32 v190, -1, v2
	s_mov_b32 s73, 0
	v_lshrrev_b32_e32 v176, 3, v0
	v_bfe_u32 v177, v0, 4, 3
	v_and_b32_e32 v184, 7, v0
	v_xor_b32_e32 v177, v184, v177
	v_lshlrev_b32_e32 v176, 8, v176
	v_lshl_or_b32 v176, v177, 4, v176
	v_mov_b32_e32 v177, 0
	v_readfirstlane_b32 s101, v0
	s_lshr_b32 s101, s101, 6
	s_lshl_b32 s101, s101, 10
	v_lshrrev_b32_e32 v253, 3, v0
	v_bfe_u32 v186, v0, 4, 3
	v_and_b32_e32 v187, 7, v0
	v_xor_b32_e32 v186, v187, v186
	v_lshlrev_b32_e32 v253, 7, v253
	v_lshl_or_b32 v178, v186, 4, v253
	v_mov_b32_e32 v179, 0
	v_add_u32_e32 v253, 16, v178
	s_branch .LBB0_1306

; #define K_LOAD(kt) do { sk0 = *(const bf16x8*)(kg + (size_t)(kt) * 8192); sk1 = *(const bf16x8*)(kg + (size_t)(kt) * 8192 + 4096); } while (0)
; #define V_LOAD(kt) do { sv0 = *(const bf16x8*)(vg + (size_t)(kt) * 8192); sv1 = *(const bf16x8*)(vg + (size_t)(kt) * 8192 + 4096); } while (0)
; #define K_STORE(bi) do { char* s_ = kbuf + (bi) * 16384; *(bf16x8*)(s_ + klds) = sk0; *(bf16x8*)(s_ + klds + 4096) = sk1; } while (0)
; DEVI void attn_item(const Params& p, const int l, const int bh, const int qblk, const float lam, const float osc, char* smem) {
;     ...
;   bf16x8 qf[4];
;   {
;     const u16* qp = PBC + (tok0 + (size_t)qblk * 128 + qg * 32 + l31) * 1280 + 512 + h * 128 + m * 64 + hi * 8;
; #pragma unroll
;     for (int d0 = 0; d0 < 4; ++d0) qf[d0] = *(const bf16x8*)(qp + d0 * 16);
;   }
;   const int kkey = tid >> 4, kch = tid & 15;
;   const u16* kg = KT + kkey * 128 + kch * 8;
;   const int klds = (kch >> 3) * 8192 + swz(kkey, kch & 7);
;   const int ve = tid >> 3, vj = tid & 7;
;   const u16* vg = VT + ve * 64 + vj * 8;
;   const int vx = (ve >> 1) & 7;
;   const int vlds0 = 16384 + ve * 128 + ((((vj >> 1) * 2 + 0) ^ vx) << 4) + (vj & 1) * 8;
;   const int vlds1 = 16384 + ve * 128 + ((((vj >> 1) * 2 + 1) ^ vx) << 4) + (vj & 1) * 8;
;   bf16x8 sk0, sk1, sv0, sv1;
;   char* kbuf = stg; char* vbuf = stg + 32768;
;     ...
;   f32x16 o[4];
; #pragma unroll
;   for (int d0 = 0; d0 < 4; ++d0)
; #pragma unroll
;     for (int r = 0; r < 16; ++r) o[d0][r] = 0.f;
;   float m_reg = -1e30f, l_reg = 0.f;
;   const int xq = (l31 >> 1) & 7;
;   f32x16 pA0, pA1, pB0, pB1;
;   K_LOAD(0); V_LOAD(0);
;   {
;     const bf16x8 tk0 = *(const bf16x8*)(kg + (size_t)8192), tk1 = *(const bf16x8*)(kg + (size_t)8192 + 4096);
;     K_STORE(0); V_STORE(0);
;     sk0 = tk0; sk1 = tk1; K_STORE(1);
;   }
;   __syncthreads();
;   QK_TILE(pA0, pA1, 0);
;   __syncthreads();
;     ...
;         if (threadIdx.x == 0) s_item = atomicAdd(cnt + q, 1);
;         __syncthreads();
;         const int item = s_item;
;         __syncthreads();
;         if (item >= 192) break;
;         int bh, qblk;
;         if (item < 128) { bh = q; qblk = 127 - item; }
;         else { bh = 8 + (q >> 1); qblk = 127 - 2 * (item - 128) - (q & 1); }
;         attn_item(p, l, bh, qblk, lam, osc, smem);
.LBB0_1313:
	s_or_b64 exec, exec, s[8:9]
	s_waitcnt lgkmcnt(0)
	s_barrier
	ds_read_b32 v2, v169
	s_mov_b64 s[8:9], -1
	s_waitcnt lgkmcnt(0)
	s_barrier
	v_cmp_lt_i32_e32 vcc, s34, v2
	v_readfirstlane_b32 s14, v2
	s_cbranch_vccnz .LBB0_1308
	s_lshl_b32 s9, s14, 1
	s_or_b32 s9, s9, s76
	s_sub_i32 s8, 0x7f, s14
	s_sub_i32 s9, 0x17f, s9
	s_cmpk_lt_i32 s14, 0x80
	s_cselect_b32 s14, s8, s9
	s_cselect_b32 s40, s74, s75
	s_lshl_b32 s77, s14, 1
	s_cmp_gt_u32 s40, 5
	s_cselect_b32 s38, 0x4000, 0
	s_lshl_b64 s[8:9], s[14:15], 7
	s_add_u32 s38, s8, s38
	s_addc_u32 s39, s9, 0
	s_lshl_b32 s8, s40, 7
	s_add_i32 s9, s8, 0xfffffd00
	s_cmp_lt_u32 s40, 6
	s_cselect_b32 s14, s8, s9
	s_lshl_b32 s8, s40, 22
	s_mov_b32 s9, s15
	v_lshl_add_u64 v[20:21], v[170:171], 0, s[8:9]
	v_add_co_u32_e32 v12, vcc, s68, v20
	v_lshl_add_u64 v[10:11], v[172:173], 0, s[8:9]
	s_nop 0
	v_addc_co_u32_e32 v13, vcc, 0, v21, vcc
	v_add_co_u32_e32 v14, vcc, s68, v10
	v_or_b32_e32 v24, s38, v166
	s_nop 0
	v_addc_co_u32_e32 v15, vcc, 0, v11, vcc
	v_mov_b64_e32 v[18:19], s[28:29]
	v_add_co_u32_e32 v22, vcc, s35, v20
	v_mad_u64_u32 v[18:19], s[40:41], v24, s36, v[18:19]
	s_nop 0
	v_addc_co_u32_e32 v23, vcc, 0, v21, vcc
	global_load_dwordx4 v[2:5], v[20:21], off
	global_load_dwordx4 v[6:9], v[10:11], off
	v_add_co_u32_e32 v20, vcc, s69, v20
	v_mad_u32_u24 v19, s39, v208, v19
	global_load_dwordx4 v[10:13], v[12:13], off
	s_nop 0
	global_load_dwordx4 v[14:17], v[14:15], off
	v_addc_co_u32_e32 v21, vcc, 0, v21, vcc
	global_load_dwordx4 v[146:149], v[22:23], off
	global_load_dwordx4 v[150:153], v[20:21], off
	v_lshl_add_u64 v[18:19], s[14:15], 1, v[18:19]
	v_mov_b32_e32 v181, v169
	v_lshl_add_u64 v[18:19], v[18:19], 0, v[180:181]
	v_mov_b32_e32 v183, v169
	v_lshl_add_u64 v[18:19], v[18:19], 0, v[182:183]
	v_add_co_u32_e32 v20, vcc, s37, v18
	v_add_u32_e32 v181, v198, v199
	s_nop 0
	v_addc_co_u32_e32 v21, vcc, 0, v19, vcc
	global_load_dwordx4 v[130:133], v[20:21], off offset:1024
	v_lshl_add_u64 v[18:19], v[18:19], 0, s[16:17]
	global_load_dwordx4 v[134:137], v[18:19], off offset:32
	global_load_dwordx4 v[138:141], v[18:19], off offset:64
	global_load_dwordx4 v[142:145], v[18:19], off offset:96
	v_add_u32_e32 v183, v198, v200
	v_add_u32_e32 v212, v198, v201
	v_add_u32_e32 v213, v198, v202
	s_mov_b32 s52, 0
	s_mov_b32 s53, s52
	s_mov_b32 s54, s52
	s_mov_b32 s55, s52
	s_mov_b32 s56, s52
	s_mov_b32 s57, s52
	s_mov_b32 s58, s52
	s_mov_b32 s59, s52
	s_mov_b32 s60, s52
	s_mov_b32 s61, s52
	s_mov_b32 s62, s52
	s_mov_b32 s63, s52
	s_mov_b32 s64, s52
	s_mov_b32 s65, s52
	s_mov_b32 s66, s52
	s_mov_b32 s67, s52
	v_mov_b64_e32 v[50:51], s[52:53]
	v_mov_b64_e32 v[52:53], s[54:55]
	v_mov_b64_e32 v[54:55], s[56:57]
	v_mov_b64_e32 v[56:57], s[58:59]
	v_mov_b64_e32 v[58:59], s[60:61]
	v_mov_b64_e32 v[60:61], s[62:63]
	v_mov_b64_e32 v[62:63], s[64:65]
	v_mov_b64_e32 v[64:65], s[66:67]
	s_add_i32 s53, s77, 2
	s_add_u32 s40, s28, s8
	v_mov_b64_e32 v[34:35], v[50:51]
	v_mov_b64_e32 v[18:19], v[50:51]
	v_add_u32_e32 v214, s77, v194
	s_addc_u32 s41, s29, 0
	v_mov_b32_e32 v215, 0
	v_mov_b32_e32 v188, 0xf149f2ca
	v_mov_b64_e32 v[36:37], v[52:53]
	v_mov_b64_e32 v[38:39], v[54:55]
	v_mov_b64_e32 v[40:41], v[56:57]
	v_mov_b64_e32 v[42:43], v[58:59]
	v_mov_b64_e32 v[44:45], v[60:61]
	v_mov_b64_e32 v[46:47], v[62:63]
	v_mov_b64_e32 v[48:49], v[64:65]
	v_mov_b64_e32 v[20:21], v[52:53]
	s_waitcnt vmcnt(9)
	ds_write_b128 v209, v[2:5] offset:2048
	s_waitcnt vmcnt(8)
	ds_write_b128 v253, v[6:9] offset:34816
	s_waitcnt vmcnt(7)
	ds_write_b128 v209, v[10:13] offset:6144
	s_waitcnt vmcnt(6)
	ds_write_b128 v253, v[14:17] offset:43008
	s_waitcnt vmcnt(5)
	ds_write_b128 v209, v[146:149] offset:18432
	s_waitcnt vmcnt(4)
	ds_write_b128 v209, v[150:153] offset:22528
	s_waitcnt lgkmcnt(0)
	s_barrier
	ds_read_b128 v[2:5], v181 offset:2048
	ds_read_b128 v[6:9], v181 offset:6144
	s_waitcnt vmcnt(3) lgkmcnt(1)
	v_mfma_f32_32x32x16_bf16 v[66:81], v[2:5], v[130:133], 0
	v_mov_b64_e32 v[22:23], v[54:55]
	v_mov_b64_e32 v[24:25], v[56:57]
	v_mov_b64_e32 v[26:27], v[58:59]
	v_mov_b64_e32 v[28:29], v[60:61]
	v_mov_b64_e32 v[30:31], v[62:63]
	v_mov_b64_e32 v[32:33], v[64:65]
	s_waitcnt lgkmcnt(0)
	v_mfma_f32_32x32x16_bf16 v[98:113], v[6:9], v[130:133], 0
	ds_read_b128 v[2:5], v183 offset:2048
	ds_read_b128 v[6:9], v183 offset:6144
	s_waitcnt vmcnt(2) lgkmcnt(1)
	v_mfma_f32_32x32x16_bf16 v[66:81], v[2:5], v[134:137], v[66:81]
	ds_read_b128 v[2:5], v212 offset:2048
	s_waitcnt lgkmcnt(1)
	v_mfma_f32_32x32x16_bf16 v[98:113], v[6:9], v[134:137], v[98:113]
	ds_read_b128 v[6:9], v212 offset:6144
	s_waitcnt vmcnt(1) lgkmcnt(1)
	v_mfma_f32_32x32x16_bf16 v[66:81], v[2:5], v[138:141], v[66:81]
	ds_read_b128 v[2:5], v213 offset:2048
	s_waitcnt lgkmcnt(1)
	v_mfma_f32_32x32x16_bf16 v[98:113], v[6:9], v[138:141], v[98:113]
	ds_read_b128 v[6:9], v213 offset:6144
	s_waitcnt lgkmcnt(0)
	s_barrier
	s_waitcnt vmcnt(0)
	v_mfma_f32_32x32x16_bf16 v[66:81], v[2:5], v[142:145], v[66:81]
	v_mfma_f32_32x32x16_bf16 v[98:113], v[6:9], v[142:145], v[98:113]
	v_mov_b64_e32 v[2:3], v[50:51]
	v_mov_b64_e32 v[4:5], v[52:53]
	v_mov_b64_e32 v[6:7], v[54:55]
	v_mov_b64_e32 v[8:9], v[56:57]
	v_mov_b64_e32 v[10:11], v[58:59]
	v_mov_b64_e32 v[12:13], v[60:61]
	v_mov_b64_e32 v[14:15], v[62:63]
	v_mov_b64_e32 v[16:17], v[64:65]
	s_branch .LBB0_1316

.LBB0_1318:
	v_lshl_add_u64 v[186:187], s[40:41], 0, v[178:179]
	v_add_co_u32_e32 v154, vcc, 0x25a04000, v186
	s_nop 1
	v_addc_co_u32_e32 v155, vcc, 0, v187, vcc
	v_add_co_u32_e32 v158, vcc, 0x25a06000, v186
	s_nop 1
	v_addc_co_u32_e32 v159, vcc, 0, v187, vcc
	s_add_u32 m0, s101, 0xc810
	s_nop 0
	global_load_lds_dwordx4 v[154:155], off
	s_add_u32 m0, s101, 0xe810
	s_nop 0
	global_load_lds_dwordx4 v[158:159], off
	v_cmp_le_u32_e32 vcc, s52, v214
	s_and_saveexec_b64 s[8:9], vcc
	s_cbranch_execz .LBB0_1324
	ds_read_b128 v[82:85], v181 offset:18432
	ds_read_b128 v[114:117], v181 offset:22528
	s_waitcnt lgkmcnt(1)
	v_mfma_f32_32x32x16_bf16 v[82:97], v[82:85], v[130:133], 0
	v_max_f32_e32 v118, v67, v67
	v_max_f32_e32 v119, v66, v66
	v_max_f32_e32 v118, v119, v118
	v_max3_f32 v118, v118, v68, v69
	v_max3_f32 v118, v118, v70, v71
	v_max3_f32 v118, v118, v72, v73
	v_max3_f32 v118, v118, v74, v75
	v_max3_f32 v118, v118, v76, v77
	v_max3_f32 v118, v118, v78, v79
	v_max3_f32 v122, v118, v80, v81
	ds_read_b128 v[118:121], v183 offset:18432
	ds_read_b128 v[218:221], v183 offset:22528
	s_waitcnt lgkmcnt(1)
	v_mfma_f32_32x32x16_bf16 v[82:97], v[118:121], v[134:137], v[82:97]
	v_max3_f32 v118, v122, v98, v99
	v_max3_f32 v118, v118, v100, v101
	v_max3_f32 v118, v118, v102, v103
	v_max3_f32 v118, v118, v104, v105
	v_max3_f32 v118, v118, v106, v107
	v_max3_f32 v118, v118, v108, v109
	v_max3_f32 v118, v118, v110, v111
	v_max3_f32 v122, v118, v112, v113
	v_mov_b32_e32 v118, v122
	s_nop 1
	v_permlane32_swap_b32_e32 v122, v118
	ds_read_b128 v[222:225], v212 offset:22528
	ds_read_b128 v[226:229], v213 offset:22528
	v_max_f32_e32 v123, v118, v118
	ds_read_b128 v[118:121], v212 offset:18432
	s_waitcnt lgkmcnt(0)
	v_mfma_f32_32x32x16_bf16 v[82:97], v[118:121], v[138:141], v[82:97]
	v_max_f32_e32 v118, v122, v122
	v_max_f32_e32 v118, v118, v123
	v_sub_f32_e32 v120, v118, v188
	v_cmp_ge_f32_e32 vcc, s70, v120
	v_max_f32_e32 v119, v188, v188
	s_cmp_eq_u64 vcc, exec
	v_max_f32_e32 v118, v119, v118
	s_cselect_b64 vcc, -1, 0
	v_cndmask_b32_e32 v216, v118, v188, vcc
	v_sub_f32_e32 v118, v188, v216
	v_mul_f32_e32 v188, 0xbe38aa3b, v216
	v_mul_f32_e32 v189, 0x3e38aa3b, v118
	ds_read_b128 v[118:121], v213 offset:18432
	s_waitcnt lgkmcnt(0)
	v_mfma_f32_32x32x16_bf16 v[82:97], v[118:121], v[142:145], v[82:97]
	v_fma_f32 v66, v66, s18, v188
	v_fma_f32 v67, v67, s18, v188
	v_fma_f32 v68, v68, s18, v188
	v_fma_f32 v69, v69, s18, v188
	v_exp_f32_e32 v66, v66
	v_exp_f32_e32 v67, v67
	v_pk_fma_f32 v[70:71], v[70:71], s[18:19], v[188:189] op_sel_hi:[1,0,0]
	v_exp_f32_e32 v68, v68
	v_exp_f32_e32 v69, v69
	v_pk_fma_f32 v[72:73], v[72:73], s[18:19], v[188:189] op_sel_hi:[1,0,0]
	v_exp_f32_e32 v70, v70
	v_exp_f32_e32 v71, v71
	v_pk_fma_f32 v[74:75], v[74:75], s[18:19], v[188:189] op_sel_hi:[1,0,0]
	v_exp_f32_e32 v72, v72
	v_exp_f32_e32 v73, v73
	v_exp_f32_e32 v74, v74
	v_exp_f32_e32 v75, v75
	v_pk_add_f32 v[118:119], v[66:67], 0 op_sel_hi:[1,0]
	v_exp_f32_e32 v217, v189
	v_pk_add_f32 v[118:119], v[68:69], v[118:119]
	s_nop 0
	v_pk_add_f32 v[118:119], v[70:71], v[118:119]
	s_nop 0
	v_pk_add_f32 v[118:119], v[72:73], v[118:119]
	s_nop 0
	v_pk_add_f32 v[230:231], v[74:75], v[118:119]
	v_mfma_f32_32x32x16_bf16 v[114:129], v[114:117], v[130:133], 0
	v_mfma_f32_32x32x16_bf16 v[114:129], v[218:221], v[134:137], v[114:129]
	v_mfma_f32_32x32x16_bf16 v[114:129], v[222:225], v[138:141], v[114:129]
	v_mfma_f32_32x32x16_bf16 v[114:129], v[226:229], v[142:145], v[114:129]
	v_fma_f32 v76, v76, s18, v188
	v_fma_f32 v77, v77, s18, v188
	v_fma_f32 v78, v78, s18, v188
	v_fma_f32 v79, v79, s18, v188
	v_exp_f32_e32 v76, v76
	v_exp_f32_e32 v77, v77
	v_pk_fma_f32 v[80:81], v[80:81], s[18:19], v[188:189] op_sel_hi:[1,0,0]
	v_exp_f32_e32 v78, v78
	v_exp_f32_e32 v79, v79
	v_exp_f32_e32 v80, v80
	v_exp_f32_e32 v81, v81
	v_pk_fma_f32 v[98:99], v[98:99], s[18:19], v[188:189] op_sel_hi:[1,0,0]
	v_pk_fma_f32 v[100:101], v[100:101], s[18:19], v[188:189] op_sel_hi:[1,0,0]
	v_exp_f32_e32 v98, v98
	v_exp_f32_e32 v99, v99
	v_pk_add_f32 v[230:231], v[76:77], v[230:231]
	v_exp_f32_e32 v100, v100
	v_exp_f32_e32 v101, v101
	v_pk_add_f32 v[230:231], v[78:79], v[230:231]
	s_nop 0
	v_pk_add_f32 v[230:231], v[80:81], v[230:231]
	s_nop 0
	v_pk_add_f32 v[230:231], v[98:99], v[230:231]
	s_nop 0
	v_pk_add_f32 v[230:231], v[100:101], v[230:231]
	v_pk_fma_f32 v[102:103], v[102:103], s[18:19], v[188:189] op_sel_hi:[1,0,0]
	v_pk_fma_f32 v[104:105], v[104:105], s[18:19], v[188:189] op_sel_hi:[1,0,0]
	v_exp_f32_e32 v102, v102
	v_exp_f32_e32 v103, v103
	v_exp_f32_e32 v104, v104
	v_exp_f32_e32 v105, v105
	v_pk_fma_f32 v[106:107], v[106:107], s[18:19], v[188:189] op_sel_hi:[1,0,0]
	v_pk_fma_f32 v[108:109], v[108:109], s[18:19], v[188:189] op_sel_hi:[1,0,0]
	v_exp_f32_e32 v106, v106
	v_exp_f32_e32 v107, v107
	v_exp_f32_e32 v108, v108
	v_exp_f32_e32 v109, v109
	v_pk_fma_f32 v[110:111], v[110:111], s[18:19], v[188:189] op_sel_hi:[1,0,0]
	v_pk_add_f32 v[218:219], v[102:103], v[230:231]
	v_exp_f32_e32 v110, v110
	v_exp_f32_e32 v111, v111
	v_pk_add_f32 v[218:219], v[104:105], v[218:219]
	s_nop 0
	v_pk_add_f32 v[218:219], v[106:107], v[218:219]
	s_nop 0
	v_pk_add_f32 v[218:219], v[108:109], v[218:219]
	s_nop 0
	v_pk_add_f32 v[218:219], v[110:111], v[218:219]
	v_pk_fma_f32 v[112:113], v[112:113], s[18:19], v[188:189] op_sel_hi:[1,0,0]
	s_nop 0
	v_exp_f32_e32 v112, v112
	v_exp_f32_e32 v113, v113
	s_nop 0
	v_pk_add_f32 v[188:189], v[112:113], v[218:219]
	s_nop 0
	v_pk_add_f32 v[188:189], v[188:189], v[188:189] op_sel:[0,1] op_sel_hi:[1,0]
	s_nop 0
	v_mov_b32_e32 v189, v188
	s_nop 1
	v_permlane32_swap_b32_e32 v188, v189
	s_cbranch_vccnz .LBB0_1323
	s_waitcnt lgkmcnt(0)
	s_and_saveexec_b64 s[56:57], s[2:3]
	ds_write_b32 v204, v217
	s_or_b64 exec, exec, s[56:57]
	s_waitcnt lgkmcnt(0)
	v_add_u32_e32 v230, v203, v191
	ds_read_b128 v[218:221], v230 offset:96
	ds_read_b128 v[222:225], v230 offset:64
	ds_read_b128 v[226:229], v230 offset:32
	ds_read_b128 v[230:233], v230
	s_waitcnt lgkmcnt(0)
	s_waitcnt lgkmcnt(3)
	v_pk_mul_f32 v[62:63], v[62:63], v[218:219]
	s_waitcnt lgkmcnt(2)
	v_pk_mul_f32 v[58:59], v[58:59], v[222:223]
	s_waitcnt lgkmcnt(1)
	v_pk_mul_f32 v[54:55], v[54:55], v[226:227]
	v_pk_mul_f32 v[64:65], v[64:65], v[220:221]
	v_pk_mul_f32 v[60:61], v[60:61], v[224:225]
	v_pk_mul_f32 v[56:57], v[56:57], v[228:229]
	s_waitcnt lgkmcnt(0)
	v_pk_mul_f32 v[52:53], v[52:53], v[232:233]
	v_pk_mul_f32 v[50:51], v[50:51], v[230:231]
	v_pk_mul_f32 v[46:47], v[46:47], v[218:219]
	v_pk_mul_f32 v[42:43], v[42:43], v[222:223]
	v_pk_mul_f32 v[38:39], v[38:39], v[226:227]
	v_pk_mul_f32 v[48:49], v[48:49], v[220:221]
	v_pk_mul_f32 v[44:45], v[44:45], v[224:225]
	v_pk_mul_f32 v[40:41], v[40:41], v[228:229]
	v_pk_mul_f32 v[36:37], v[36:37], v[232:233]
	v_pk_mul_f32 v[34:35], v[34:35], v[230:231]
	v_pk_mul_f32 v[30:31], v[30:31], v[218:219]
	v_pk_mul_f32 v[26:27], v[26:27], v[222:223]
	v_pk_mul_f32 v[22:23], v[22:23], v[226:227]
	v_pk_mul_f32 v[32:33], v[32:33], v[220:221]
	v_pk_mul_f32 v[28:29], v[28:29], v[224:225]
	v_pk_mul_f32 v[24:25], v[24:25], v[228:229]
	v_pk_mul_f32 v[20:21], v[20:21], v[232:233]
	v_pk_mul_f32 v[18:19], v[18:19], v[230:231]
	v_pk_mul_f32 v[14:15], v[14:15], v[218:219]
	v_pk_mul_f32 v[10:11], v[10:11], v[222:223]
	v_pk_mul_f32 v[6:7], v[6:7], v[226:227]
	v_pk_mul_f32 v[16:17], v[16:17], v[220:221]
	v_pk_mul_f32 v[12:13], v[12:13], v[224:225]
	v_pk_mul_f32 v[8:9], v[8:9], v[228:229]
	v_pk_mul_f32 v[4:5], v[4:5], v[232:233]
	v_pk_mul_f32 v[2:3], v[2:3], v[230:231]

; DEVI void attn_item(const Params& p, const int l, const int bh, const int qblk, const float lam, const float osc, char* smem) {
;     ...
;   for (int kt = 0; kt < nkt; kt += 2) {
;     ATT_ITER(kt, pA0, pA1, pB0, pB1);
;     ATT_ITER(kt + 1, pB0, pB1, pA0, pA1);
.LBB0_1326:
	s_add_i32 s56, s52, 3
	s_cmp_lt_u32 s56, s53
	s_cselect_b64 s[54:55], -1, 0
	s_cmp_ge_u32 s56, s53
	s_waitcnt vmcnt(0)
	s_waitcnt lgkmcnt(0)
	s_barrier
	s_cbranch_scc0 .LBB0_1331
	s_and_b64 vcc, exec, s[8:9]
	s_cbranch_vccz .LBB0_1332

.LBB0_1332:
	v_add_co_u32_e32 v154, vcc, 0x25a08000, v186
	s_nop 1
	v_addc_co_u32_e32 v155, vcc, 0, v187, vcc
	v_add_co_u32_e32 v158, vcc, 0x25a0a000, v186
	s_nop 1
	v_addc_co_u32_e32 v159, vcc, 0, v187, vcc
	s_add_u32 m0, s101, 0x8810
	s_nop 0
	global_load_lds_dwordx4 v[154:155], off
	s_add_u32 m0, s101, 0xa810
	s_nop 0
	global_load_lds_dwordx4 v[158:159], off
	v_cmp_lt_u32_e32 vcc, s52, v214
	s_and_saveexec_b64 s[56:57], vcc
	s_cbranch_execz .LBB0_1329
